# v61 + K-loop MFMA segments trimmed: no-op s_setprio 0/1 pair between the two 16-MFMA clusters and the second redundant s_waitcnt lgkmcnt(0) after the barrier removed
# speedup vs baseline: 1.0204x; 1.0204x over previous
; #define PG8_STAGE(bufoff, gbase, voff) do { _Pragma("unroll") for (int _i = 0; _i < 2; ++_i) \
;         __builtin_amdgcn_global_load_lds((const unsigned*)((const char*)(gbase) + (voff)[_i]), (LAS unsigned*)(lds + (bufoff) + ldsw + _i * 8192), 16, 0, 0); } while (0)
; #define PG8_LDA(dst, b, h) do { _Pragma("unroll") for (int m = 0; m < 4; ++m) _Pragma("unroll") for (int k = 0; k < 2; ++k) dst[m][k] = *(const LAS bf16x8*)(lds + PG8_SA(b, h) + aoff + m * 2048 + k * 1024); } while (0)
; #define PG8_LDB(dst, b, h) do { _Pragma("unroll") for (int n = 0; n < 2; ++n) _Pragma("unroll") for (int k = 0; k < 2; ++k) dst[n][k] = *(const LAS bf16x8*)(lds + PG8_SB(b, h) + boff + n * 2048 + k * 1024); } while (0)
; #define PG8_MMA(ai, bj, At, Bt) do { __builtin_amdgcn_s_setprio(1); _Pragma("unroll") for (int m = 0; m < 4; ++m) _Pragma("unroll") for (int n = 0; n < 2; ++n) _Pragma("unroll") for (int k = 0; k < 2; ++k) \
;         acc[ai][bj][m][n] = __builtin_amdgcn_mfma_f32_16x16x32_bf16(Bt[n][k], At[m][k], acc[ai][bj][m][n], 0, 0, 0); __builtin_amdgcn_s_setprio(0); } while (0)
; #define PG8_WAIT_V(n) asm volatile("s_waitcnt vmcnt(" #n ")" ::: "memory")
; #define PG8_WAIT_L(n) asm volatile("s_waitcnt lgkmcnt(" #n ")" ::: "memory")
; #define PG8_BAR __builtin_amdgcn_s_barrier()
; template <class Epi, class Sched>
; __device__ __forceinline__ void gemm_phase(LAS unsigned char* lds, const Gemm g, const Sched& S, const Epi& E) {
;     ...
;         for (int t = 0; t < nt; t += 2) {
;             const bool last = (t == nt - 2);
;             const char* a1 = cA + (size_t)(t + 1) * kstep;
;             const char* a2 = last ? nA : cA + (size_t)(t + 2) * kstep; const char* b2 = last ? nB : cB + (size_t)(t + 2) * kstep;
;             const char* a3 = a2 + kstep; const char* b3 = b2 + kstep;
;             if (last && has_next) S.a_ready(nxt);
;             PG8_LDB(B0, 0, 0); PG8_LDB(B1, 0, 1); PG8_SCHED; PG8_LDA(At, 0, 0); PG8_STAGE(PG8_SA(1, 1), a1 + hstep, voffA);
;             PG8_WAIT_V(8); PG8_WAIT_L(0); PG8_BAR; PG8_MMA(0, 0, At, B0); PG8_MMA(0, 1, At, B1); PG8_BAR; PG8_SCHED;
;             PG8_LDA(At, 0, 1); PG8_STAGE(PG8_SB(0, 0), b2, voffB); PG8_STAGE(PG8_SB(0, 1), b2 + hstep, voffB); PG8_STAGE(PG8_SA(0, 0), a2, voffA);
;             PG8_WAIT_V(8); PG8_WAIT_L(0); PG8_BAR; PG8_MMA(1, 0, At, B0); PG8_MMA(1, 1, At, B1); PG8_BAR; PG8_SCHED;
.LBB0_131:
	s_add_i32 s58, s50, 2
	s_add_u32 s48, s46, 0x100
	s_addc_u32 s49, s47, 0
	s_add_u32 s1, s9, s46
	s_addc_u32 s51, s36, s47
	s_cmp_eq_u32 s56, s50
	s_cselect_b32 s50, 0, s48
	s_cselect_b32 s59, 0, s49
	s_cselect_b32 s60, s44, s1
	s_cselect_b32 s61, s45, s51
	s_add_u32 s50, s2, s50
	s_addc_u32 s51, s3, s59
	s_add_i32 s1, 0, 0x10000
	s_add_i32 s59, 0, 0x14000
	v_add_u32_e32 v156, s1, v142
	v_add_u32_e32 v172, s59, v142
	ds_read_b128 v[144:147], v156
	ds_read_b128 v[148:151], v156 offset:1024
	ds_read_b128 v[152:155], v156 offset:2048
	ds_read_b128 v[156:159], v156 offset:3072
	ds_read_b128 v[160:163], v172
	ds_read_b128 v[164:167], v172 offset:1024
	ds_read_b128 v[168:171], v172 offset:2048
	ds_read_b128 v[172:175], v172 offset:3072
	s_add_u32 s46, s46, s2
	s_addc_u32 s47, s47, s3
	s_add_u32 s46, s46, s20
	s_addc_u32 s47, s47, s21
	s_add_u32 s46, s46, 0x80
	s_addc_u32 s47, s47, 0
	s_add_i32 m0, s5, 0xc000
	ds_read_b128 v[176:179], v143
	ds_read_b128 v[180:183], v143 offset:1024
	ds_read_b128 v[184:187], v143 offset:2048
	ds_read_b128 v[192:195], v143 offset:3072
	ds_read_b128 v[196:199], v143 offset:4096
	ds_read_b128 v[200:203], v143 offset:5120
	ds_read_b128 v[204:207], v143 offset:6144
	ds_read_b128 v[208:211], v143 offset:7168
	global_load_lds_dwordx4 v134, s[46:47]
	s_add_i32 m0, s5, 0xe000
	s_nop 0
	global_load_lds_dwordx4 v132, s[46:47]
	s_waitcnt vmcnt(8)
	s_waitcnt lgkmcnt(0)
	s_barrier
	s_setprio 1
	v_mfma_f32_16x16x32_bf16 v[122:125], v[144:147], v[176:179], v[122:125]
	v_mfma_f32_16x16x32_bf16 v[126:129], v[152:155], v[176:179], v[126:129]
	v_mfma_f32_16x16x32_bf16 v[110:113], v[144:147], v[184:187], v[110:113]
	v_mfma_f32_16x16x32_bf16 v[106:109], v[152:155], v[184:187], v[106:109]
	v_mfma_f32_16x16x32_bf16 v[94:97], v[144:147], v[196:199], v[94:97]
	v_mfma_f32_16x16x32_bf16 v[90:93], v[152:155], v[196:199], v[90:93]
	v_mfma_f32_16x16x32_bf16 v[78:81], v[144:147], v[204:207], v[78:81]
	v_mfma_f32_16x16x32_bf16 v[74:77], v[152:155], v[204:207], v[74:77]
	v_mfma_f32_16x16x32_bf16 v[122:125], v[148:151], v[180:183], v[122:125]
	v_mfma_f32_16x16x32_bf16 v[126:129], v[156:159], v[180:183], v[126:129]
	v_mfma_f32_16x16x32_bf16 v[110:113], v[148:151], v[192:195], v[110:113]
	v_mfma_f32_16x16x32_bf16 v[106:109], v[156:159], v[192:195], v[106:109]
	v_mfma_f32_16x16x32_bf16 v[94:97], v[148:151], v[200:203], v[94:97]
	v_mfma_f32_16x16x32_bf16 v[90:93], v[156:159], v[200:203], v[90:93]
	v_mfma_f32_16x16x32_bf16 v[78:81], v[148:151], v[208:211], v[78:81]
	v_mfma_f32_16x16x32_bf16 v[74:77], v[156:159], v[208:211], v[74:77]
	v_mfma_f32_16x16x32_bf16 v[118:121], v[160:163], v[176:179], v[118:121]
	v_mfma_f32_16x16x32_bf16 v[114:117], v[168:171], v[176:179], v[114:117]
	v_mfma_f32_16x16x32_bf16 v[102:105], v[160:163], v[184:187], v[102:105]
	v_mfma_f32_16x16x32_bf16 v[98:101], v[168:171], v[184:187], v[98:101]
	v_mfma_f32_16x16x32_bf16 v[86:89], v[160:163], v[196:199], v[86:89]
	v_mfma_f32_16x16x32_bf16 v[82:85], v[168:171], v[196:199], v[82:85]
	v_mfma_f32_16x16x32_bf16 v[70:73], v[160:163], v[204:207], v[70:73]
	v_mfma_f32_16x16x32_bf16 v[66:69], v[168:171], v[204:207], v[66:69]
	v_mfma_f32_16x16x32_bf16 v[118:121], v[164:167], v[180:183], v[118:121]
	v_mfma_f32_16x16x32_bf16 v[114:117], v[172:175], v[180:183], v[114:117]
	v_mfma_f32_16x16x32_bf16 v[102:105], v[164:167], v[192:195], v[102:105]
	v_mfma_f32_16x16x32_bf16 v[98:101], v[172:175], v[192:195], v[98:101]
	v_mfma_f32_16x16x32_bf16 v[86:89], v[164:167], v[200:203], v[86:89]
	v_mfma_f32_16x16x32_bf16 v[82:85], v[172:175], v[200:203], v[82:85]
	v_mfma_f32_16x16x32_bf16 v[70:73], v[164:167], v[208:211], v[70:73]
	v_mfma_f32_16x16x32_bf16 v[66:69], v[172:175], v[208:211], v[66:69]
	s_setprio 0
	s_barrier
	s_add_i32 s1, s1, s4
	s_mov_b32 m0, s1
	ds_read_b128 v[176:179], v143 offset:16384
	ds_read_b128 v[180:183], v143 offset:17408
	ds_read_b128 v[184:187], v143 offset:18432
	ds_read_b128 v[192:195], v143 offset:19456
	ds_read_b128 v[196:199], v143 offset:20480
	ds_read_b128 v[200:203], v143 offset:21504
	ds_read_b128 v[204:207], v143 offset:22528
	ds_read_b128 v[208:211], v143 offset:23552
	global_load_lds_dwordx4 v0, s[60:61]
	s_add_i32 m0, s1, 0x2000
	s_add_u32 s46, s60, s20
	s_addc_u32 s47, s61, s21
	s_add_i32 s1, s59, s4
	global_load_lds_dwordx4 v130, s[60:61]
	s_mov_b32 m0, s1
	s_nop 0
	global_load_lds_dwordx4 v0, s[46:47]
	s_add_i32 m0, s1, 0x2000
	s_nop 0
	global_load_lds_dwordx4 v130, s[46:47]
	s_mov_b32 m0, s5
	s_nop 0
	global_load_lds_dwordx4 v134, s[50:51]
	s_mov_b32 m0, s18
	s_nop 0
	global_load_lds_dwordx4 v132, s[50:51]
	s_waitcnt vmcnt(8)
	s_waitcnt lgkmcnt(0)
	s_barrier
; #define PG8_STAGE(bufoff, gbase, voff) do { _Pragma("unroll") for (int _i = 0; _i < 2; ++_i) \
;         __builtin_amdgcn_global_load_lds((const unsigned*)((const char*)(gbase) + (voff)[_i]), (LAS unsigned*)(lds + (bufoff) + ldsw + _i * 8192), 16, 0, 0); } while (0)
; #define PG8_LDA(dst, b, h) do { _Pragma("unroll") for (int m = 0; m < 4; ++m) _Pragma("unroll") for (int k = 0; k < 2; ++k) dst[m][k] = *(const LAS bf16x8*)(lds + PG8_SA(b, h) + aoff + m * 2048 + k * 1024); } while (0)
; #define PG8_LDB(dst, b, h) do { _Pragma("unroll") for (int n = 0; n < 2; ++n) _Pragma("unroll") for (int k = 0; k < 2; ++k) dst[n][k] = *(const LAS bf16x8*)(lds + PG8_SB(b, h) + boff + n * 2048 + k * 1024); } while (0)
; #define PG8_MMA(ai, bj, At, Bt) do { __builtin_amdgcn_s_setprio(1); _Pragma("unroll") for (int m = 0; m < 4; ++m) _Pragma("unroll") for (int n = 0; n < 2; ++n) _Pragma("unroll") for (int k = 0; k < 2; ++k) \
;         acc[ai][bj][m][n] = __builtin_amdgcn_mfma_f32_16x16x32_bf16(Bt[n][k], At[m][k], acc[ai][bj][m][n], 0, 0, 0); __builtin_amdgcn_s_setprio(0); } while (0)
; #define PG8_WAIT_V(n) asm volatile("s_waitcnt vmcnt(" #n ")" ::: "memory")
; #define PG8_WAIT_L(n) asm volatile("s_waitcnt lgkmcnt(" #n ")" ::: "memory")
; #define PG8_BAR __builtin_amdgcn_s_barrier()
; #define PG8_SCHED __builtin_amdgcn_sched_barrier(0)
; template <class Epi, class Sched>
; __device__ __forceinline__ void gemm_phase(LAS unsigned char* lds, const Gemm g, const Sched& S, const Epi& E) {
;     ...
;             PG8_WAIT_V(8); PG8_WAIT_L(0); PG8_BAR; PG8_MMA(1, 0, At, B0); PG8_MMA(1, 1, At, B1); PG8_BAR; PG8_SCHED;
;             PG8_LDB(B0, 1, 0); PG8_LDB(B1, 1, 1); PG8_SCHED; PG8_LDA(At, 1, 0); PG8_STAGE(PG8_SA(0, 1), a2 + hstep, voffA);
;             PG8_WAIT_V(8); PG8_WAIT_L(0); PG8_BAR; PG8_MMA(0, 0, At, B0); PG8_MMA(0, 1, At, B1); PG8_BAR; PG8_SCHED;
	s_setprio 1
	v_mfma_f32_16x16x32_bf16 v[62:65], v[144:147], v[176:179], v[62:65]
	v_mfma_f32_16x16x32_bf16 v[58:61], v[152:155], v[176:179], v[58:61]
	v_mfma_f32_16x16x32_bf16 v[46:49], v[144:147], v[184:187], v[46:49]
	v_mfma_f32_16x16x32_bf16 v[42:45], v[152:155], v[184:187], v[42:45]
	v_mfma_f32_16x16x32_bf16 v[30:33], v[144:147], v[196:199], v[30:33]
	v_mfma_f32_16x16x32_bf16 v[26:29], v[152:155], v[196:199], v[26:29]
	v_mfma_f32_16x16x32_bf16 v[14:17], v[144:147], v[204:207], v[14:17]
	v_mfma_f32_16x16x32_bf16 v[10:13], v[152:155], v[204:207], v[10:13]
	v_mfma_f32_16x16x32_bf16 v[62:65], v[148:151], v[180:183], v[62:65]
	v_mfma_f32_16x16x32_bf16 v[58:61], v[156:159], v[180:183], v[58:61]
	v_mfma_f32_16x16x32_bf16 v[46:49], v[148:151], v[192:195], v[46:49]
	v_mfma_f32_16x16x32_bf16 v[42:45], v[156:159], v[192:195], v[42:45]
	v_mfma_f32_16x16x32_bf16 v[30:33], v[148:151], v[200:203], v[30:33]
	v_mfma_f32_16x16x32_bf16 v[26:29], v[156:159], v[200:203], v[26:29]
	v_mfma_f32_16x16x32_bf16 v[14:17], v[148:151], v[208:211], v[14:17]
	v_mfma_f32_16x16x32_bf16 v[10:13], v[156:159], v[208:211], v[10:13]
	v_mfma_f32_16x16x32_bf16 v[54:57], v[160:163], v[176:179], v[54:57]
	v_mfma_f32_16x16x32_bf16 v[50:53], v[168:171], v[176:179], v[50:53]
	v_mfma_f32_16x16x32_bf16 v[38:41], v[160:163], v[184:187], v[38:41]
	v_mfma_f32_16x16x32_bf16 v[34:37], v[168:171], v[184:187], v[34:37]
	v_mfma_f32_16x16x32_bf16 v[22:25], v[160:163], v[196:199], v[22:25]
	v_mfma_f32_16x16x32_bf16 v[18:21], v[168:171], v[196:199], v[18:21]
	v_mfma_f32_16x16x32_bf16 v[6:9], v[160:163], v[204:207], v[6:9]
	v_mfma_f32_16x16x32_bf16 v[2:5], v[168:171], v[204:207], v[2:5]
	v_mfma_f32_16x16x32_bf16 v[54:57], v[164:167], v[180:183], v[54:57]
	v_mfma_f32_16x16x32_bf16 v[50:53], v[172:175], v[180:183], v[50:53]
	v_mfma_f32_16x16x32_bf16 v[38:41], v[164:167], v[192:195], v[38:41]
	v_mfma_f32_16x16x32_bf16 v[34:37], v[172:175], v[192:195], v[34:37]
	v_mfma_f32_16x16x32_bf16 v[22:25], v[164:167], v[200:203], v[22:25]
	v_mfma_f32_16x16x32_bf16 v[18:21], v[172:175], v[200:203], v[18:21]
	v_mfma_f32_16x16x32_bf16 v[6:9], v[164:167], v[208:211], v[6:9]
	v_mfma_f32_16x16x32_bf16 v[2:5], v[172:175], v[208:211], v[2:5]
	s_setprio 0
	s_barrier
	s_add_i32 s1, 0, 0x18000
	s_add_i32 s59, 0, 0x1c000
	v_add_u32_e32 v156, s1, v142
	v_add_u32_e32 v172, s59, v142
	ds_read_b128 v[144:147], v156
	ds_read_b128 v[148:151], v156 offset:1024
	ds_read_b128 v[152:155], v156 offset:2048
	ds_read_b128 v[156:159], v156 offset:3072
	ds_read_b128 v[160:163], v172
	ds_read_b128 v[164:167], v172 offset:1024
	ds_read_b128 v[168:171], v172 offset:2048
	ds_read_b128 v[172:175], v172 offset:3072
	s_add_u32 s46, s50, s20
	s_addc_u32 s47, s51, s21
	s_mov_b32 m0, s19
	ds_read_b128 v[176:179], v143 offset:32768
	ds_read_b128 v[180:183], v143 offset:33792
	ds_read_b128 v[184:187], v143 offset:34816
	ds_read_b128 v[192:195], v143 offset:35840
	ds_read_b128 v[196:199], v143 offset:36864
	ds_read_b128 v[200:203], v143 offset:37888
	ds_read_b128 v[204:207], v143 offset:38912
	ds_read_b128 v[208:211], v143 offset:39936
	global_load_lds_dwordx4 v134, s[46:47]
	s_mov_b32 m0, s52
	s_nop 0
	global_load_lds_dwordx4 v132, s[46:47]
	s_waitcnt vmcnt(8)
	s_waitcnt lgkmcnt(0)
	s_barrier
	s_setprio 1
	v_mfma_f32_16x16x32_bf16 v[122:125], v[144:147], v[176:179], v[122:125]
	v_mfma_f32_16x16x32_bf16 v[126:129], v[152:155], v[176:179], v[126:129]
	v_mfma_f32_16x16x32_bf16 v[110:113], v[144:147], v[184:187], v[110:113]
	v_mfma_f32_16x16x32_bf16 v[106:109], v[152:155], v[184:187], v[106:109]
	v_mfma_f32_16x16x32_bf16 v[94:97], v[144:147], v[196:199], v[94:97]
	v_mfma_f32_16x16x32_bf16 v[90:93], v[152:155], v[196:199], v[90:93]
	v_mfma_f32_16x16x32_bf16 v[78:81], v[144:147], v[204:207], v[78:81]
	v_mfma_f32_16x16x32_bf16 v[74:77], v[152:155], v[204:207], v[74:77]
	v_mfma_f32_16x16x32_bf16 v[122:125], v[148:151], v[180:183], v[122:125]
	v_mfma_f32_16x16x32_bf16 v[126:129], v[156:159], v[180:183], v[126:129]
	v_mfma_f32_16x16x32_bf16 v[110:113], v[148:151], v[192:195], v[110:113]
	v_mfma_f32_16x16x32_bf16 v[106:109], v[156:159], v[192:195], v[106:109]
	v_mfma_f32_16x16x32_bf16 v[94:97], v[148:151], v[200:203], v[94:97]
	v_mfma_f32_16x16x32_bf16 v[90:93], v[156:159], v[200:203], v[90:93]
	v_mfma_f32_16x16x32_bf16 v[78:81], v[148:151], v[208:211], v[78:81]
	v_mfma_f32_16x16x32_bf16 v[74:77], v[156:159], v[208:211], v[74:77]
	v_mfma_f32_16x16x32_bf16 v[118:121], v[160:163], v[176:179], v[118:121]
	v_mfma_f32_16x16x32_bf16 v[114:117], v[168:171], v[176:179], v[114:117]
	v_mfma_f32_16x16x32_bf16 v[102:105], v[160:163], v[184:187], v[102:105]
	v_mfma_f32_16x16x32_bf16 v[98:101], v[168:171], v[184:187], v[98:101]
	v_mfma_f32_16x16x32_bf16 v[86:89], v[160:163], v[196:199], v[86:89]
	v_mfma_f32_16x16x32_bf16 v[82:85], v[168:171], v[196:199], v[82:85]
	v_mfma_f32_16x16x32_bf16 v[70:73], v[160:163], v[204:207], v[70:73]
	v_mfma_f32_16x16x32_bf16 v[66:69], v[168:171], v[204:207], v[66:69]
	v_mfma_f32_16x16x32_bf16 v[118:121], v[164:167], v[180:183], v[118:121]
	v_mfma_f32_16x16x32_bf16 v[114:117], v[172:175], v[180:183], v[114:117]
	v_mfma_f32_16x16x32_bf16 v[102:105], v[164:167], v[192:195], v[102:105]
	v_mfma_f32_16x16x32_bf16 v[98:101], v[172:175], v[192:195], v[98:101]
	v_mfma_f32_16x16x32_bf16 v[86:89], v[164:167], v[200:203], v[86:89]
	v_mfma_f32_16x16x32_bf16 v[82:85], v[172:175], v[200:203], v[82:85]
	v_mfma_f32_16x16x32_bf16 v[70:73], v[164:167], v[208:211], v[70:73]
	v_mfma_f32_16x16x32_bf16 v[66:69], v[172:175], v[208:211], v[66:69]
	s_setprio 0
	s_barrier
; #define PG8_STAGE(bufoff, gbase, voff) do { _Pragma("unroll") for (int _i = 0; _i < 2; ++_i) \
;         __builtin_amdgcn_global_load_lds((const unsigned*)((const char*)(gbase) + (voff)[_i]), (LAS unsigned*)(lds + (bufoff) + ldsw + _i * 8192), 16, 0, 0); } while (0)
; #define PG8_LDA(dst, b, h) do { _Pragma("unroll") for (int m = 0; m < 4; ++m) _Pragma("unroll") for (int k = 0; k < 2; ++k) dst[m][k] = *(const LAS bf16x8*)(lds + PG8_SA(b, h) + aoff + m * 2048 + k * 1024); } while (0)
; #define PG8_MMA(ai, bj, At, Bt) do { __builtin_amdgcn_s_setprio(1); _Pragma("unroll") for (int m = 0; m < 4; ++m) _Pragma("unroll") for (int n = 0; n < 2; ++n) _Pragma("unroll") for (int k = 0; k < 2; ++k) \
;         acc[ai][bj][m][n] = __builtin_amdgcn_mfma_f32_16x16x32_bf16(Bt[n][k], At[m][k], acc[ai][bj][m][n], 0, 0, 0); __builtin_amdgcn_s_setprio(0); } while (0)
; #define PG8_WAIT_V(n) asm volatile("s_waitcnt vmcnt(" #n ")" ::: "memory")
; #define PG8_WAIT_L(n) asm volatile("s_waitcnt lgkmcnt(" #n ")" ::: "memory")
; #define PG8_BAR __builtin_amdgcn_s_barrier()
; #define PG8_SCHED __builtin_amdgcn_sched_barrier(0)
; template <class Epi, class Sched>
; __device__ __forceinline__ void gemm_phase(LAS unsigned char* lds, const Gemm g, const Sched& S, const Epi& E) {
;     ...
;             PG8_LDA(At, 1, 1); PG8_STAGE(PG8_SB(1, 0), b3, voffB); PG8_STAGE(PG8_SB(1, 1), b3 + hstep, voffB); PG8_STAGE(PG8_SA(1, 0), a3, voffA);
;             PG8_WAIT_V(8); PG8_WAIT_L(0); PG8_BAR; PG8_MMA(1, 0, At, B0); PG8_MMA(1, 1, At, B1); PG8_BAR; PG8_SCHED;
;         }
	s_add_i32 s1, s1, s4
	s_add_u32 s46, s60, 0x80
	s_addc_u32 s47, s61, 0
	s_mov_b32 m0, s1
	ds_read_b128 v[176:179], v143 offset:49152
	ds_read_b128 v[180:183], v143 offset:50176
	ds_read_b128 v[184:187], v143 offset:51200
	ds_read_b128 v[192:195], v143 offset:52224
	ds_read_b128 v[196:199], v143 offset:53248
	ds_read_b128 v[200:203], v143 offset:54272
	ds_read_b128 v[204:207], v143 offset:55296
	ds_read_b128 v[208:211], v143 offset:56320
	global_load_lds_dwordx4 v0, s[46:47]
	s_add_i32 m0, s1, 0x2000
	s_add_i32 s1, s59, s4
	global_load_lds_dwordx4 v130, s[46:47]
	s_add_u32 s46, s46, s20
	s_addc_u32 s47, s47, s21
	s_mov_b32 m0, s1
	s_nop 0
	global_load_lds_dwordx4 v0, s[46:47]
	s_add_i32 m0, s1, 0x2000
	s_nop 0
	global_load_lds_dwordx4 v130, s[46:47]
	s_add_u32 s46, s50, 0x80
	s_addc_u32 s47, s51, 0
	s_mov_b32 m0, s53
	s_nop 0
	global_load_lds_dwordx4 v134, s[46:47]
	s_mov_b32 m0, s54
	s_nop 0
	global_load_lds_dwordx4 v132, s[46:47]
	s_waitcnt vmcnt(8)
	s_waitcnt lgkmcnt(0)
	s_barrier
	s_setprio 1
	v_mfma_f32_16x16x32_bf16 v[62:65], v[144:147], v[176:179], v[62:65]
	v_mfma_f32_16x16x32_bf16 v[58:61], v[152:155], v[176:179], v[58:61]
	v_mfma_f32_16x16x32_bf16 v[46:49], v[144:147], v[184:187], v[46:49]
	v_mfma_f32_16x16x32_bf16 v[42:45], v[152:155], v[184:187], v[42:45]
	v_mfma_f32_16x16x32_bf16 v[30:33], v[144:147], v[196:199], v[30:33]
	v_mfma_f32_16x16x32_bf16 v[26:29], v[152:155], v[196:199], v[26:29]
	v_mfma_f32_16x16x32_bf16 v[14:17], v[144:147], v[204:207], v[14:17]
	v_mfma_f32_16x16x32_bf16 v[10:13], v[152:155], v[204:207], v[10:13]
	v_mfma_f32_16x16x32_bf16 v[62:65], v[148:151], v[180:183], v[62:65]
	v_mfma_f32_16x16x32_bf16 v[58:61], v[156:159], v[180:183], v[58:61]
	v_mfma_f32_16x16x32_bf16 v[46:49], v[148:151], v[192:195], v[46:49]
	v_mfma_f32_16x16x32_bf16 v[42:45], v[156:159], v[192:195], v[42:45]
	v_mfma_f32_16x16x32_bf16 v[30:33], v[148:151], v[200:203], v[30:33]
	v_mfma_f32_16x16x32_bf16 v[26:29], v[156:159], v[200:203], v[26:29]
	v_mfma_f32_16x16x32_bf16 v[14:17], v[148:151], v[208:211], v[14:17]
	v_mfma_f32_16x16x32_bf16 v[10:13], v[156:159], v[208:211], v[10:13]
	v_mfma_f32_16x16x32_bf16 v[54:57], v[160:163], v[176:179], v[54:57]
	v_mfma_f32_16x16x32_bf16 v[50:53], v[168:171], v[176:179], v[50:53]
	v_mfma_f32_16x16x32_bf16 v[38:41], v[160:163], v[184:187], v[38:41]
	v_mfma_f32_16x16x32_bf16 v[34:37], v[168:171], v[184:187], v[34:37]
	v_mfma_f32_16x16x32_bf16 v[22:25], v[160:163], v[196:199], v[22:25]
	v_mfma_f32_16x16x32_bf16 v[18:21], v[168:171], v[196:199], v[18:21]
	v_mfma_f32_16x16x32_bf16 v[6:9], v[160:163], v[204:207], v[6:9]
	v_mfma_f32_16x16x32_bf16 v[2:5], v[168:171], v[204:207], v[2:5]
	v_mfma_f32_16x16x32_bf16 v[54:57], v[164:167], v[180:183], v[54:57]
	v_mfma_f32_16x16x32_bf16 v[50:53], v[172:175], v[180:183], v[50:53]
	v_mfma_f32_16x16x32_bf16 v[38:41], v[164:167], v[192:195], v[38:41]
	v_mfma_f32_16x16x32_bf16 v[34:37], v[172:175], v[192:195], v[34:37]
	v_mfma_f32_16x16x32_bf16 v[22:25], v[164:167], v[200:203], v[22:25]
	v_mfma_f32_16x16x32_bf16 v[18:21], v[172:175], v[200:203], v[18:21]
	v_mfma_f32_16x16x32_bf16 v[6:9], v[164:167], v[208:211], v[6:9]
	v_mfma_f32_16x16x32_bf16 v[2:5], v[172:175], v[208:211], v[2:5]
	s_setprio 0
	s_barrier
	s_cmp_ge_i32 s58, s55
	s_mov_b64 s[46:47], s[48:49]
	s_mov_b32 s50, s58
	s_cbranch_scc0 .LBB0_131

; #define PG8_STAGE(bufoff, gbase, voff) do { _Pragma("unroll") for (int _i = 0; _i < 2; ++_i) \
;         __builtin_amdgcn_global_load_lds((const unsigned*)((const char*)(gbase) + (voff)[_i]), (LAS unsigned*)(lds + (bufoff) + ldsw + _i * 8192), 16, 0, 0); } while (0)
; #define PG8_LDA(dst, b, h) do { _Pragma("unroll") for (int m = 0; m < 4; ++m) _Pragma("unroll") for (int k = 0; k < 2; ++k) dst[m][k] = *(const LAS bf16x8*)(lds + PG8_SA(b, h) + aoff + m * 2048 + k * 1024); } while (0)
; #define PG8_LDB(dst, b, h) do { _Pragma("unroll") for (int n = 0; n < 2; ++n) _Pragma("unroll") for (int k = 0; k < 2; ++k) dst[n][k] = *(const LAS bf16x8*)(lds + PG8_SB(b, h) + boff + n * 2048 + k * 1024); } while (0)
; #define PG8_MMA(ai, bj, At, Bt) do { __builtin_amdgcn_s_setprio(1); _Pragma("unroll") for (int m = 0; m < 4; ++m) _Pragma("unroll") for (int n = 0; n < 2; ++n) _Pragma("unroll") for (int k = 0; k < 2; ++k) \
;         acc[ai][bj][m][n] = __builtin_amdgcn_mfma_f32_16x16x32_bf16(Bt[n][k], At[m][k], acc[ai][bj][m][n], 0, 0, 0); __builtin_amdgcn_s_setprio(0); } while (0)
; #define PG8_WAIT_V(n) asm volatile("s_waitcnt vmcnt(" #n ")" ::: "memory")
; #define PG8_WAIT_L(n) asm volatile("s_waitcnt lgkmcnt(" #n ")" ::: "memory")
; #define PG8_BAR __builtin_amdgcn_s_barrier()
; #define PG8_SCHED __builtin_amdgcn_sched_barrier(0)
; template <class Epi, class Sched>
; __device__ __forceinline__ void gemm_phase(LAS unsigned char* lds, const Gemm g, const Sched& S, const Epi& E) {
;     ...
;         for (int t = 0; t < nt; t += 2) {
;             const bool last = (t == nt - 2);
;             const char* a1 = cA + (size_t)(t + 1) * kstep;
;             const char* a2 = last ? nA : cA + (size_t)(t + 2) * kstep; const char* b2 = last ? nB : cB + (size_t)(t + 2) * kstep;
;             const char* a3 = a2 + kstep; const char* b3 = b2 + kstep;
;             if (last && has_next) S.a_ready(nxt);
;             PG8_LDB(B0, 0, 0); PG8_LDB(B1, 0, 1); PG8_SCHED; PG8_LDA(At, 0, 0); PG8_STAGE(PG8_SA(1, 1), a1 + hstep, voffA);
;             PG8_WAIT_V(8); PG8_WAIT_L(0); PG8_BAR; PG8_MMA(0, 0, At, B0); PG8_MMA(0, 1, At, B1); PG8_BAR; PG8_SCHED;
;             PG8_LDA(At, 0, 1); PG8_STAGE(PG8_SB(0, 0), b2, voffB); PG8_STAGE(PG8_SB(0, 1), b2 + hstep, voffB); PG8_STAGE(PG8_SA(0, 0), a2, voffA);
.LBB0_406:
	s_add_i32 s48, s44, 2
	s_add_u32 s42, s40, 0x100
	s_addc_u32 s43, s41, 0
	s_cmp_lg_u32 s47, s44
	s_cselect_b32 s49, s42, 0
	s_cselect_b32 s1, s43, 0
	s_add_u32 s44, s10, s49
	s_addc_u32 s45, s11, s1
	s_add_i32 s52, 0, 0x10000
	s_add_u32 s50, s26, s49
	v_add_u32_e32 v136, s52, v107
	s_addc_u32 s51, s27, s1
	s_add_i32 s1, 0, 0x14000
	ds_read_b128 v[146:149], v136
	ds_read_b128 v[150:153], v136 offset:1024
	ds_read_b128 v[154:157], v136 offset:2048
	ds_read_b128 v[158:161], v136 offset:3072
	v_add_u32_e32 v136, s1, v107
	ds_read_b128 v[162:165], v136
	ds_read_b128 v[166:169], v136 offset:1024
	ds_read_b128 v[170:173], v136 offset:2048
	ds_read_b128 v[174:177], v136 offset:3072
	v_lshl_add_u64 v[136:137], v[130:131], 0, s[40:41]
	s_add_i32 m0, s9, 0xc000
	ds_read_b128 v[178:181], v135
	ds_read_b128 v[182:185], v135 offset:1024
	ds_read_b128 v[192:195], v135 offset:2048
	ds_read_b128 v[196:199], v135 offset:3072
	ds_read_b128 v[200:203], v135 offset:4096
	ds_read_b128 v[204:207], v135 offset:5120
	ds_read_b128 v[208:211], v135 offset:6144
	ds_read_b128 v[212:215], v135 offset:7168
	global_load_lds_dwordx4 v[136:137], off
	v_lshl_add_u64 v[136:137], v[132:133], 0, s[40:41]
	s_add_i32 m0, s9, 0xe000
	s_nop 0
	global_load_lds_dwordx4 v[136:137], off
	s_waitcnt vmcnt(8)
	s_waitcnt lgkmcnt(0)
	s_barrier
	s_setprio 1
	v_mfma_f32_16x16x32_bf16 v[142:145], v[146:149], v[178:181], v[142:145]
	v_mfma_f32_16x16x32_bf16 v[136:139], v[154:157], v[178:181], v[138:141]
	v_mfma_f32_16x16x32_bf16 v[114:117], v[146:149], v[192:195], v[114:117]
	v_mfma_f32_16x16x32_bf16 v[110:113], v[154:157], v[192:195], v[110:113]
	v_mfma_f32_16x16x32_bf16 v[94:97], v[146:149], v[200:203], v[94:97]
	v_mfma_f32_16x16x32_bf16 v[90:93], v[154:157], v[200:203], v[90:93]
	v_mfma_f32_16x16x32_bf16 v[78:81], v[146:149], v[208:211], v[78:81]
	v_mfma_f32_16x16x32_bf16 v[74:77], v[154:157], v[208:211], v[74:77]
	v_mfma_f32_16x16x32_bf16 v[142:145], v[150:153], v[182:185], v[142:145]
	v_mfma_f32_16x16x32_bf16 v[136:139], v[158:161], v[182:185], v[136:139]
	v_mfma_f32_16x16x32_bf16 v[114:117], v[150:153], v[196:199], v[114:117]
	v_mfma_f32_16x16x32_bf16 v[110:113], v[158:161], v[196:199], v[110:113]
	v_mfma_f32_16x16x32_bf16 v[94:97], v[150:153], v[204:207], v[94:97]
	v_mfma_f32_16x16x32_bf16 v[90:93], v[158:161], v[204:207], v[90:93]
	v_mfma_f32_16x16x32_bf16 v[78:81], v[150:153], v[212:215], v[78:81]
	v_mfma_f32_16x16x32_bf16 v[74:77], v[158:161], v[212:215], v[74:77]
	v_mfma_f32_16x16x32_bf16 v[126:129], v[162:165], v[178:181], v[126:129]
	v_mfma_f32_16x16x32_bf16 v[122:125], v[170:173], v[178:181], v[122:125]
	v_mfma_f32_16x16x32_bf16 v[102:105], v[162:165], v[192:195], v[102:105]
	v_mfma_f32_16x16x32_bf16 v[98:101], v[170:173], v[192:195], v[98:101]
	v_mfma_f32_16x16x32_bf16 v[86:89], v[162:165], v[200:203], v[86:89]
	v_mfma_f32_16x16x32_bf16 v[82:85], v[170:173], v[200:203], v[82:85]
	v_mfma_f32_16x16x32_bf16 v[70:73], v[162:165], v[208:211], v[70:73]
	v_mfma_f32_16x16x32_bf16 v[66:69], v[170:173], v[208:211], v[66:69]
	v_mfma_f32_16x16x32_bf16 v[126:129], v[166:169], v[182:185], v[126:129]
	v_mfma_f32_16x16x32_bf16 v[122:125], v[174:177], v[182:185], v[122:125]
	v_mfma_f32_16x16x32_bf16 v[102:105], v[166:169], v[196:199], v[102:105]
	v_mfma_f32_16x16x32_bf16 v[98:101], v[174:177], v[196:199], v[98:101]
	v_mfma_f32_16x16x32_bf16 v[86:89], v[166:169], v[204:207], v[86:89]
	v_mfma_f32_16x16x32_bf16 v[82:85], v[174:177], v[204:207], v[82:85]
	v_mfma_f32_16x16x32_bf16 v[70:73], v[166:169], v[212:215], v[70:73]
	v_mfma_f32_16x16x32_bf16 v[66:69], v[174:177], v[212:215], v[66:69]
	s_setprio 0
	s_barrier
	s_add_i32 s40, s52, s8
	v_lshl_add_u64 v[186:187], s[50:51], 0, v[0:1]
	s_mov_b32 m0, s40
	ds_read_b128 v[178:181], v135 offset:16384
	ds_read_b128 v[182:185], v135 offset:17408
	ds_read_b128 v[192:195], v135 offset:18432
	ds_read_b128 v[196:199], v135 offset:19456
	ds_read_b128 v[200:203], v135 offset:20480
	ds_read_b128 v[204:207], v135 offset:21504
	ds_read_b128 v[208:211], v135 offset:22528
	ds_read_b128 v[212:215], v135 offset:23552
	global_load_lds_dwordx4 v[186:187], off
	s_add_i32 m0, s40, 0x2000
	s_add_u32 s40, s50, s38
	v_lshl_add_u64 v[216:217], s[50:51], 0, v[108:109]
	s_addc_u32 s41, s51, s39
	s_add_i32 s1, s1, s8
	global_load_lds_dwordx4 v[216:217], off
	v_lshl_add_u64 v[238:239], s[40:41], 0, v[0:1]
	s_mov_b32 m0, s1
	v_lshl_add_u64 v[240:241], s[40:41], 0, v[108:109]
	global_load_lds_dwordx4 v[238:239], off
	s_add_i32 m0, s1, 0x2000
	v_lshl_add_u64 v[244:245], s[44:45], 0, v[120:121]
	global_load_lds_dwordx4 v[240:241], off
	s_mov_b32 m0, s9
	v_lshl_add_u64 v[246:247], s[44:45], 0, v[118:119]
	global_load_lds_dwordx4 v[244:245], off
	s_mov_b32 m0, s18
	s_nop 0
	global_load_lds_dwordx4 v[246:247], off
	s_waitcnt vmcnt(8)
	s_waitcnt lgkmcnt(0)
	s_barrier
; #define PG8_STAGE(bufoff, gbase, voff) do { _Pragma("unroll") for (int _i = 0; _i < 2; ++_i) \
;         __builtin_amdgcn_global_load_lds((const unsigned*)((const char*)(gbase) + (voff)[_i]), (LAS unsigned*)(lds + (bufoff) + ldsw + _i * 8192), 16, 0, 0); } while (0)
; #define PG8_LDA(dst, b, h) do { _Pragma("unroll") for (int m = 0; m < 4; ++m) _Pragma("unroll") for (int k = 0; k < 2; ++k) dst[m][k] = *(const LAS bf16x8*)(lds + PG8_SA(b, h) + aoff + m * 2048 + k * 1024); } while (0)
; #define PG8_LDB(dst, b, h) do { _Pragma("unroll") for (int n = 0; n < 2; ++n) _Pragma("unroll") for (int k = 0; k < 2; ++k) dst[n][k] = *(const LAS bf16x8*)(lds + PG8_SB(b, h) + boff + n * 2048 + k * 1024); } while (0)
; #define PG8_MMA(ai, bj, At, Bt) do { __builtin_amdgcn_s_setprio(1); _Pragma("unroll") for (int m = 0; m < 4; ++m) _Pragma("unroll") for (int n = 0; n < 2; ++n) _Pragma("unroll") for (int k = 0; k < 2; ++k) \
;         acc[ai][bj][m][n] = __builtin_amdgcn_mfma_f32_16x16x32_bf16(Bt[n][k], At[m][k], acc[ai][bj][m][n], 0, 0, 0); __builtin_amdgcn_s_setprio(0); } while (0)
; #define PG8_WAIT_V(n) asm volatile("s_waitcnt vmcnt(" #n ")" ::: "memory")
; #define PG8_WAIT_L(n) asm volatile("s_waitcnt lgkmcnt(" #n ")" ::: "memory")
; #define PG8_BAR __builtin_amdgcn_s_barrier()
; #define PG8_SCHED __builtin_amdgcn_sched_barrier(0)
; template <class Epi, class Sched>
; __device__ __forceinline__ void gemm_phase(LAS unsigned char* lds, const Gemm g, const Sched& S, const Epi& E) {
;     ...
;             PG8_WAIT_V(8); PG8_WAIT_L(0); PG8_BAR; PG8_MMA(1, 0, At, B0); PG8_MMA(1, 1, At, B1); PG8_BAR; PG8_SCHED;
;             PG8_LDB(B0, 1, 0); PG8_LDB(B1, 1, 1); PG8_SCHED; PG8_LDA(At, 1, 0); PG8_STAGE(PG8_SA(0, 1), a2 + hstep, voffA);
;             PG8_WAIT_V(8); PG8_WAIT_L(0); PG8_BAR; PG8_MMA(0, 0, At, B0); PG8_MMA(0, 1, At, B1); PG8_BAR; PG8_SCHED;
	s_setprio 1
	v_mfma_f32_16x16x32_bf16 v[62:65], v[146:149], v[178:181], v[62:65]
	v_mfma_f32_16x16x32_bf16 v[58:61], v[154:157], v[178:181], v[58:61]
	v_mfma_f32_16x16x32_bf16 v[46:49], v[146:149], v[192:195], v[46:49]
	v_mfma_f32_16x16x32_bf16 v[42:45], v[154:157], v[192:195], v[42:45]
	v_mfma_f32_16x16x32_bf16 v[30:33], v[146:149], v[200:203], v[30:33]
	v_mfma_f32_16x16x32_bf16 v[26:29], v[154:157], v[200:203], v[26:29]
	v_mfma_f32_16x16x32_bf16 v[14:17], v[146:149], v[208:211], v[14:17]
	v_mfma_f32_16x16x32_bf16 v[10:13], v[154:157], v[208:211], v[10:13]
	v_mfma_f32_16x16x32_bf16 v[62:65], v[150:153], v[182:185], v[62:65]
	v_mfma_f32_16x16x32_bf16 v[58:61], v[158:161], v[182:185], v[58:61]
	v_mfma_f32_16x16x32_bf16 v[46:49], v[150:153], v[196:199], v[46:49]
	v_mfma_f32_16x16x32_bf16 v[42:45], v[158:161], v[196:199], v[42:45]
	v_mfma_f32_16x16x32_bf16 v[30:33], v[150:153], v[204:207], v[30:33]
	v_mfma_f32_16x16x32_bf16 v[26:29], v[158:161], v[204:207], v[26:29]
	v_mfma_f32_16x16x32_bf16 v[14:17], v[150:153], v[212:215], v[14:17]
	v_mfma_f32_16x16x32_bf16 v[10:13], v[158:161], v[212:215], v[10:13]
	v_mfma_f32_16x16x32_bf16 v[54:57], v[162:165], v[178:181], v[54:57]
	v_mfma_f32_16x16x32_bf16 v[50:53], v[170:173], v[178:181], v[50:53]
	v_mfma_f32_16x16x32_bf16 v[38:41], v[162:165], v[192:195], v[38:41]
	v_mfma_f32_16x16x32_bf16 v[34:37], v[170:173], v[192:195], v[34:37]
	v_mfma_f32_16x16x32_bf16 v[22:25], v[162:165], v[200:203], v[22:25]
	v_mfma_f32_16x16x32_bf16 v[18:21], v[170:173], v[200:203], v[18:21]
	v_mfma_f32_16x16x32_bf16 v[6:9], v[162:165], v[208:211], v[6:9]
	v_mfma_f32_16x16x32_bf16 v[2:5], v[170:173], v[208:211], v[2:5]
	v_mfma_f32_16x16x32_bf16 v[54:57], v[166:169], v[182:185], v[54:57]
	v_mfma_f32_16x16x32_bf16 v[50:53], v[174:177], v[182:185], v[50:53]
	v_mfma_f32_16x16x32_bf16 v[38:41], v[166:169], v[196:199], v[38:41]
	v_mfma_f32_16x16x32_bf16 v[34:37], v[174:177], v[196:199], v[34:37]
	v_mfma_f32_16x16x32_bf16 v[22:25], v[166:169], v[204:207], v[22:25]
	v_mfma_f32_16x16x32_bf16 v[18:21], v[174:177], v[204:207], v[18:21]
	v_mfma_f32_16x16x32_bf16 v[6:9], v[166:169], v[212:215], v[6:9]
	v_mfma_f32_16x16x32_bf16 v[2:5], v[174:177], v[212:215], v[2:5]
	s_setprio 0
	s_barrier
	s_add_i32 s1, 0, 0x18000
	v_add_u32_e32 v140, s1, v107
	s_add_i32 s49, 0, 0x1c000
	ds_read_b128 v[146:149], v140
	ds_read_b128 v[150:153], v140 offset:1024
	ds_read_b128 v[154:157], v140 offset:2048
	ds_read_b128 v[158:161], v140 offset:3072
	v_add_u32_e32 v140, s49, v107
	ds_read_b128 v[162:165], v140
	ds_read_b128 v[166:169], v140 offset:1024
	ds_read_b128 v[170:173], v140 offset:2048
	ds_read_b128 v[174:177], v140 offset:3072
	s_add_u32 s40, s44, s38
	s_addc_u32 s41, s45, s39
	s_mov_b32 m0, s19
	v_lshl_add_u64 v[140:141], s[40:41], 0, v[120:121]
	ds_read_b128 v[178:181], v135 offset:32768
	ds_read_b128 v[182:185], v135 offset:33792
	ds_read_b128 v[192:195], v135 offset:34816
	ds_read_b128 v[196:199], v135 offset:35840
	ds_read_b128 v[200:203], v135 offset:36864
	ds_read_b128 v[204:207], v135 offset:37888
	ds_read_b128 v[208:211], v135 offset:38912
	ds_read_b128 v[212:215], v135 offset:39936
	global_load_lds_dwordx4 v[140:141], off
	v_lshl_add_u64 v[140:141], s[40:41], 0, v[118:119]
	s_mov_b32 m0, s20
	s_nop 0
	global_load_lds_dwordx4 v[140:141], off
	s_waitcnt vmcnt(8)
	s_waitcnt lgkmcnt(0)
	s_barrier
	s_setprio 1
	v_mfma_f32_16x16x32_bf16 v[140:143], v[146:149], v[178:181], v[142:145]
	v_mfma_f32_16x16x32_bf16 v[136:139], v[154:157], v[178:181], v[136:139]
	v_mfma_f32_16x16x32_bf16 v[114:117], v[146:149], v[192:195], v[114:117]
	v_mfma_f32_16x16x32_bf16 v[110:113], v[154:157], v[192:195], v[110:113]
	v_mfma_f32_16x16x32_bf16 v[94:97], v[146:149], v[200:203], v[94:97]
	v_mfma_f32_16x16x32_bf16 v[90:93], v[154:157], v[200:203], v[90:93]
	v_mfma_f32_16x16x32_bf16 v[78:81], v[146:149], v[208:211], v[78:81]
	v_mfma_f32_16x16x32_bf16 v[74:77], v[154:157], v[208:211], v[74:77]
	v_mfma_f32_16x16x32_bf16 v[142:145], v[150:153], v[182:185], v[140:143]
	v_mfma_f32_16x16x32_bf16 v[138:141], v[158:161], v[182:185], v[136:139]
	v_mfma_f32_16x16x32_bf16 v[114:117], v[150:153], v[196:199], v[114:117]
	v_mfma_f32_16x16x32_bf16 v[110:113], v[158:161], v[196:199], v[110:113]
	v_mfma_f32_16x16x32_bf16 v[94:97], v[150:153], v[204:207], v[94:97]
	v_mfma_f32_16x16x32_bf16 v[90:93], v[158:161], v[204:207], v[90:93]
	v_mfma_f32_16x16x32_bf16 v[78:81], v[150:153], v[212:215], v[78:81]
	v_mfma_f32_16x16x32_bf16 v[74:77], v[158:161], v[212:215], v[74:77]
	v_mfma_f32_16x16x32_bf16 v[126:129], v[162:165], v[178:181], v[126:129]
	v_mfma_f32_16x16x32_bf16 v[122:125], v[170:173], v[178:181], v[122:125]
	v_mfma_f32_16x16x32_bf16 v[102:105], v[162:165], v[192:195], v[102:105]
	v_mfma_f32_16x16x32_bf16 v[98:101], v[170:173], v[192:195], v[98:101]
	v_mfma_f32_16x16x32_bf16 v[86:89], v[162:165], v[200:203], v[86:89]
	v_mfma_f32_16x16x32_bf16 v[82:85], v[170:173], v[200:203], v[82:85]
	v_mfma_f32_16x16x32_bf16 v[70:73], v[162:165], v[208:211], v[70:73]
	v_mfma_f32_16x16x32_bf16 v[66:69], v[170:173], v[208:211], v[66:69]
	v_mfma_f32_16x16x32_bf16 v[126:129], v[166:169], v[182:185], v[126:129]
	v_mfma_f32_16x16x32_bf16 v[122:125], v[174:177], v[182:185], v[122:125]
	v_mfma_f32_16x16x32_bf16 v[102:105], v[166:169], v[196:199], v[102:105]
	v_mfma_f32_16x16x32_bf16 v[98:101], v[174:177], v[196:199], v[98:101]
	v_mfma_f32_16x16x32_bf16 v[86:89], v[166:169], v[204:207], v[86:89]
	v_mfma_f32_16x16x32_bf16 v[82:85], v[174:177], v[204:207], v[82:85]
	v_mfma_f32_16x16x32_bf16 v[70:73], v[166:169], v[212:215], v[70:73]
	v_mfma_f32_16x16x32_bf16 v[66:69], v[174:177], v[212:215], v[66:69]
	s_setprio 0
	s_barrier
; #define PG8_STAGE(bufoff, gbase, voff) do { _Pragma("unroll") for (int _i = 0; _i < 2; ++_i) \
;         __builtin_amdgcn_global_load_lds((const unsigned*)((const char*)(gbase) + (voff)[_i]), (LAS unsigned*)(lds + (bufoff) + ldsw + _i * 8192), 16, 0, 0); } while (0)
; #define PG8_LDA(dst, b, h) do { _Pragma("unroll") for (int m = 0; m < 4; ++m) _Pragma("unroll") for (int k = 0; k < 2; ++k) dst[m][k] = *(const LAS bf16x8*)(lds + PG8_SA(b, h) + aoff + m * 2048 + k * 1024); } while (0)
; #define PG8_MMA(ai, bj, At, Bt) do { __builtin_amdgcn_s_setprio(1); _Pragma("unroll") for (int m = 0; m < 4; ++m) _Pragma("unroll") for (int n = 0; n < 2; ++n) _Pragma("unroll") for (int k = 0; k < 2; ++k) \
;         acc[ai][bj][m][n] = __builtin_amdgcn_mfma_f32_16x16x32_bf16(Bt[n][k], At[m][k], acc[ai][bj][m][n], 0, 0, 0); __builtin_amdgcn_s_setprio(0); } while (0)
; #define PG8_WAIT_V(n) asm volatile("s_waitcnt vmcnt(" #n ")" ::: "memory")
; #define PG8_WAIT_L(n) asm volatile("s_waitcnt lgkmcnt(" #n ")" ::: "memory")
; #define PG8_BAR __builtin_amdgcn_s_barrier()
; #define PG8_SCHED __builtin_amdgcn_sched_barrier(0)
; template <class Epi, class Sched>
; __device__ __forceinline__ void gemm_phase(LAS unsigned char* lds, const Gemm g, const Sched& S, const Epi& E) {
;     ...
;             PG8_LDA(At, 1, 1); PG8_STAGE(PG8_SB(1, 0), b3, voffB); PG8_STAGE(PG8_SB(1, 1), b3 + hstep, voffB); PG8_STAGE(PG8_SA(1, 0), a3, voffA);
;             PG8_WAIT_V(8); PG8_WAIT_L(0); PG8_BAR; PG8_MMA(1, 0, At, B0); PG8_MMA(1, 1, At, B1); PG8_BAR; PG8_SCHED;
;         }
	s_add_i32 s1, s1, s8
	v_lshl_add_u64 v[136:137], v[186:187], 0, s[6:7]
	s_mov_b32 m0, s1
	ds_read_b128 v[178:181], v135 offset:49152
	ds_read_b128 v[182:185], v135 offset:50176
	ds_read_b128 v[192:195], v135 offset:51200
	ds_read_b128 v[196:199], v135 offset:52224
	ds_read_b128 v[200:203], v135 offset:53248
	ds_read_b128 v[204:207], v135 offset:54272
	ds_read_b128 v[208:211], v135 offset:55296
	ds_read_b128 v[212:215], v135 offset:56320
	global_load_lds_dwordx4 v[136:137], off
	v_lshl_add_u64 v[136:137], v[216:217], 0, s[6:7]
	s_add_i32 m0, s1, 0x2000
	s_add_i32 s1, s49, s8
	global_load_lds_dwordx4 v[136:137], off
	v_lshl_add_u64 v[136:137], v[238:239], 0, s[6:7]
	s_mov_b32 m0, s1
	s_nop 0
	global_load_lds_dwordx4 v[136:137], off
	v_lshl_add_u64 v[136:137], v[240:241], 0, s[6:7]
	s_add_i32 m0, s1, 0x2000
	s_nop 0
	global_load_lds_dwordx4 v[136:137], off
	v_lshl_add_u64 v[136:137], v[244:245], 0, s[6:7]
	s_mov_b32 m0, s21
	s_nop 0
	global_load_lds_dwordx4 v[136:137], off
	v_lshl_add_u64 v[136:137], v[246:247], 0, s[6:7]
	s_mov_b32 m0, s36
	s_nop 0
	global_load_lds_dwordx4 v[136:137], off
	s_waitcnt vmcnt(8)
	s_waitcnt lgkmcnt(0)
	s_barrier
	s_setprio 1
	v_mfma_f32_16x16x32_bf16 v[62:65], v[146:149], v[178:181], v[62:65]
	v_mfma_f32_16x16x32_bf16 v[58:61], v[154:157], v[178:181], v[58:61]
	v_mfma_f32_16x16x32_bf16 v[46:49], v[146:149], v[192:195], v[46:49]
	v_mfma_f32_16x16x32_bf16 v[42:45], v[154:157], v[192:195], v[42:45]
	v_mfma_f32_16x16x32_bf16 v[30:33], v[146:149], v[200:203], v[30:33]
	v_mfma_f32_16x16x32_bf16 v[26:29], v[154:157], v[200:203], v[26:29]
	v_mfma_f32_16x16x32_bf16 v[14:17], v[146:149], v[208:211], v[14:17]
	v_mfma_f32_16x16x32_bf16 v[10:13], v[154:157], v[208:211], v[10:13]
	v_mfma_f32_16x16x32_bf16 v[62:65], v[150:153], v[182:185], v[62:65]
	v_mfma_f32_16x16x32_bf16 v[58:61], v[158:161], v[182:185], v[58:61]
	v_mfma_f32_16x16x32_bf16 v[46:49], v[150:153], v[196:199], v[46:49]
	v_mfma_f32_16x16x32_bf16 v[42:45], v[158:161], v[196:199], v[42:45]
	v_mfma_f32_16x16x32_bf16 v[30:33], v[150:153], v[204:207], v[30:33]
	v_mfma_f32_16x16x32_bf16 v[26:29], v[158:161], v[204:207], v[26:29]
	v_mfma_f32_16x16x32_bf16 v[14:17], v[150:153], v[212:215], v[14:17]
	v_mfma_f32_16x16x32_bf16 v[10:13], v[158:161], v[212:215], v[10:13]
	v_mfma_f32_16x16x32_bf16 v[54:57], v[162:165], v[178:181], v[54:57]
	v_mfma_f32_16x16x32_bf16 v[50:53], v[170:173], v[178:181], v[50:53]
	v_mfma_f32_16x16x32_bf16 v[38:41], v[162:165], v[192:195], v[38:41]
	v_mfma_f32_16x16x32_bf16 v[34:37], v[170:173], v[192:195], v[34:37]
	v_mfma_f32_16x16x32_bf16 v[22:25], v[162:165], v[200:203], v[22:25]
	v_mfma_f32_16x16x32_bf16 v[18:21], v[170:173], v[200:203], v[18:21]
	v_mfma_f32_16x16x32_bf16 v[6:9], v[162:165], v[208:211], v[6:9]
	v_mfma_f32_16x16x32_bf16 v[2:5], v[170:173], v[208:211], v[2:5]
	v_mfma_f32_16x16x32_bf16 v[54:57], v[166:169], v[182:185], v[54:57]
	v_mfma_f32_16x16x32_bf16 v[50:53], v[174:177], v[182:185], v[50:53]
	v_mfma_f32_16x16x32_bf16 v[38:41], v[166:169], v[196:199], v[38:41]
	v_mfma_f32_16x16x32_bf16 v[34:37], v[174:177], v[196:199], v[34:37]
	v_mfma_f32_16x16x32_bf16 v[22:25], v[166:169], v[204:207], v[22:25]
	v_mfma_f32_16x16x32_bf16 v[18:21], v[174:177], v[204:207], v[18:21]
	v_mfma_f32_16x16x32_bf16 v[6:9], v[166:169], v[212:215], v[6:9]
	v_mfma_f32_16x16x32_bf16 v[2:5], v[174:177], v[212:215], v[2:5]
	s_setprio 0
	s_barrier
	s_cmp_ge_i32 s48, s46
	s_mov_b64 s[40:41], s[42:43]
	s_mov_b32 s44, s48
	s_cbranch_scc0 .LBB0_406

; #define PG8_STAGE(bufoff, gbase, voff) do { _Pragma("unroll") for (int _i = 0; _i < 2; ++_i) \
;         __builtin_amdgcn_global_load_lds((const unsigned*)((const char*)(gbase) + (voff)[_i]), (LAS unsigned*)(lds + (bufoff) + ldsw + _i * 8192), 16, 0, 0); } while (0)
; #define PG8_LDA(dst, b, h) do { _Pragma("unroll") for (int m = 0; m < 4; ++m) _Pragma("unroll") for (int k = 0; k < 2; ++k) dst[m][k] = *(const LAS bf16x8*)(lds + PG8_SA(b, h) + aoff + m * 2048 + k * 1024); } while (0)
; #define PG8_LDB(dst, b, h) do { _Pragma("unroll") for (int n = 0; n < 2; ++n) _Pragma("unroll") for (int k = 0; k < 2; ++k) dst[n][k] = *(const LAS bf16x8*)(lds + PG8_SB(b, h) + boff + n * 2048 + k * 1024); } while (0)
; #define PG8_MMA(ai, bj, At, Bt) do { __builtin_amdgcn_s_setprio(1); _Pragma("unroll") for (int m = 0; m < 4; ++m) _Pragma("unroll") for (int n = 0; n < 2; ++n) _Pragma("unroll") for (int k = 0; k < 2; ++k) \
;         acc[ai][bj][m][n] = __builtin_amdgcn_mfma_f32_16x16x32_bf16(Bt[n][k], At[m][k], acc[ai][bj][m][n], 0, 0, 0); __builtin_amdgcn_s_setprio(0); } while (0)
; #define PG8_WAIT_V(n) asm volatile("s_waitcnt vmcnt(" #n ")" ::: "memory")
; #define PG8_WAIT_L(n) asm volatile("s_waitcnt lgkmcnt(" #n ")" ::: "memory")
; #define PG8_BAR __builtin_amdgcn_s_barrier()
; template <class Epi, class Sched>
; __device__ __forceinline__ void gemm_phase(LAS unsigned char* lds, const Gemm g, const Sched& S, const Epi& E) {
;     ...
;         for (int t = 0; t < nt; t += 2) {
;             const bool last = (t == nt - 2);
;             const char* a1 = cA + (size_t)(t + 1) * kstep;
;             const char* a2 = last ? nA : cA + (size_t)(t + 2) * kstep; const char* b2 = last ? nB : cB + (size_t)(t + 2) * kstep;
;             const char* a3 = a2 + kstep; const char* b3 = b2 + kstep;
;             if (last && has_next) S.a_ready(nxt);
;             PG8_LDB(B0, 0, 0); PG8_LDB(B1, 0, 1); PG8_SCHED; PG8_LDA(At, 0, 0); PG8_STAGE(PG8_SA(1, 1), a1 + hstep, voffA);
;             PG8_WAIT_V(8); PG8_WAIT_L(0); PG8_BAR; PG8_MMA(0, 0, At, B0); PG8_MMA(0, 1, At, B1); PG8_BAR; PG8_SCHED;
;             PG8_LDA(At, 0, 1); PG8_STAGE(PG8_SB(0, 0), b2, voffB); PG8_STAGE(PG8_SB(0, 1), b2 + hstep, voffB); PG8_STAGE(PG8_SA(0, 0), a2, voffA);
;             PG8_WAIT_V(8); PG8_WAIT_L(0); PG8_BAR; PG8_MMA(1, 0, At, B0); PG8_MMA(1, 1, At, B1); PG8_BAR; PG8_SCHED;
.LBB0_418:
	s_add_i32 s58, s52, 2
	s_add_u32 s50, s48, 0x100
	s_addc_u32 s51, s49, 0
	s_add_u32 s1, s9, s48
	s_addc_u32 s53, s36, s49
	s_cmp_eq_u32 s56, s52
	s_cselect_b32 s52, 0, s50
	s_cselect_b32 s59, 0, s51
	s_cselect_b32 s60, s46, s1
	s_cselect_b32 s61, s47, s53
	s_add_u32 s52, s2, s52
	s_addc_u32 s53, s3, s59
	s_add_i32 s1, 0, 0x10000
	s_add_i32 s59, 0, 0x14000
	v_add_u32_e32 v154, s1, v160
	v_add_u32_e32 v158, s59, v160
	ds_read_b128 v[130:133], v154
	ds_read_b128 v[134:137], v154 offset:1024
	ds_read_b128 v[138:141], v154 offset:2048
	ds_read_b128 v[154:157], v154 offset:3072
	ds_read_b128 v[162:165], v158
	ds_read_b128 v[166:169], v158 offset:1024
	ds_read_b128 v[170:173], v158 offset:2048
	ds_read_b128 v[174:177], v158 offset:3072
	s_add_u32 s48, s48, s2
	s_addc_u32 s49, s49, s3
	s_add_u32 s48, s48, s26
	s_addc_u32 s49, s49, s27
	s_add_u32 s48, s48, 0x80
	s_addc_u32 s49, s49, 0
	s_add_i32 m0, s5, 0xc000
	ds_read_b128 v[178:181], v161
	ds_read_b128 v[182:185], v161 offset:1024
	ds_read_b128 v[192:195], v161 offset:2048
	ds_read_b128 v[196:199], v161 offset:3072
	ds_read_b128 v[200:203], v161 offset:4096
	ds_read_b128 v[204:207], v161 offset:5120
	ds_read_b128 v[208:211], v161 offset:6144
	ds_read_b128 v[212:215], v161 offset:7168
	global_load_lds_dwordx4 v146, s[48:49]
	s_add_i32 m0, s5, 0xe000
	s_nop 0
	global_load_lds_dwordx4 v144, s[48:49]
	s_waitcnt vmcnt(8)
	s_waitcnt lgkmcnt(0)
	s_barrier
	s_setprio 1
	v_mfma_f32_16x16x32_bf16 v[122:125], v[130:133], v[178:181], v[122:125]
	v_mfma_f32_16x16x32_bf16 v[126:129], v[138:141], v[178:181], v[126:129]
	v_mfma_f32_16x16x32_bf16 v[110:113], v[130:133], v[192:195], v[110:113]
	v_mfma_f32_16x16x32_bf16 v[106:109], v[138:141], v[192:195], v[106:109]
	v_mfma_f32_16x16x32_bf16 v[94:97], v[130:133], v[200:203], v[94:97]
	v_mfma_f32_16x16x32_bf16 v[90:93], v[138:141], v[200:203], v[90:93]
	v_mfma_f32_16x16x32_bf16 v[78:81], v[130:133], v[208:211], v[78:81]
	v_mfma_f32_16x16x32_bf16 v[74:77], v[138:141], v[208:211], v[74:77]
	v_mfma_f32_16x16x32_bf16 v[122:125], v[134:137], v[182:185], v[122:125]
	v_mfma_f32_16x16x32_bf16 v[126:129], v[154:157], v[182:185], v[126:129]
	v_mfma_f32_16x16x32_bf16 v[110:113], v[134:137], v[196:199], v[110:113]
	v_mfma_f32_16x16x32_bf16 v[106:109], v[154:157], v[196:199], v[106:109]
	v_mfma_f32_16x16x32_bf16 v[94:97], v[134:137], v[204:207], v[94:97]
	v_mfma_f32_16x16x32_bf16 v[90:93], v[154:157], v[204:207], v[90:93]
	v_mfma_f32_16x16x32_bf16 v[78:81], v[134:137], v[212:215], v[78:81]
	v_mfma_f32_16x16x32_bf16 v[74:77], v[154:157], v[212:215], v[74:77]
	v_mfma_f32_16x16x32_bf16 v[118:121], v[162:165], v[178:181], v[118:121]
	v_mfma_f32_16x16x32_bf16 v[114:117], v[170:173], v[178:181], v[114:117]
	v_mfma_f32_16x16x32_bf16 v[102:105], v[162:165], v[192:195], v[102:105]
	v_mfma_f32_16x16x32_bf16 v[98:101], v[170:173], v[192:195], v[98:101]
	v_mfma_f32_16x16x32_bf16 v[86:89], v[162:165], v[200:203], v[86:89]
	v_mfma_f32_16x16x32_bf16 v[82:85], v[170:173], v[200:203], v[82:85]
	v_mfma_f32_16x16x32_bf16 v[70:73], v[162:165], v[208:211], v[70:73]
	v_mfma_f32_16x16x32_bf16 v[66:69], v[170:173], v[208:211], v[66:69]
	v_mfma_f32_16x16x32_bf16 v[118:121], v[166:169], v[182:185], v[118:121]
	v_mfma_f32_16x16x32_bf16 v[114:117], v[174:177], v[182:185], v[114:117]
	v_mfma_f32_16x16x32_bf16 v[102:105], v[166:169], v[196:199], v[102:105]
	v_mfma_f32_16x16x32_bf16 v[98:101], v[174:177], v[196:199], v[98:101]
	v_mfma_f32_16x16x32_bf16 v[86:89], v[166:169], v[204:207], v[86:89]
	v_mfma_f32_16x16x32_bf16 v[82:85], v[174:177], v[204:207], v[82:85]
	v_mfma_f32_16x16x32_bf16 v[70:73], v[166:169], v[212:215], v[70:73]
	v_mfma_f32_16x16x32_bf16 v[66:69], v[174:177], v[212:215], v[66:69]
	s_setprio 0
	s_barrier
	s_add_i32 s1, s1, s4
	s_mov_b32 m0, s1
	ds_read_b128 v[178:181], v161 offset:16384
	ds_read_b128 v[182:185], v161 offset:17408
	ds_read_b128 v[192:195], v161 offset:18432
	ds_read_b128 v[196:199], v161 offset:19456
	ds_read_b128 v[200:203], v161 offset:20480
	ds_read_b128 v[204:207], v161 offset:21504
	ds_read_b128 v[208:211], v161 offset:22528
	ds_read_b128 v[212:215], v161 offset:23552
	global_load_lds_dwordx4 v0, s[60:61]
	s_add_i32 m0, s1, 0x2000
	s_add_u32 s48, s60, s26
	s_addc_u32 s49, s61, s27
	s_add_i32 s1, s59, s4
	global_load_lds_dwordx4 v142, s[60:61]
	s_mov_b32 m0, s1
	s_nop 0
	global_load_lds_dwordx4 v0, s[48:49]
	s_add_i32 m0, s1, 0x2000
	s_nop 0
	global_load_lds_dwordx4 v142, s[48:49]
	s_mov_b32 m0, s5
	s_nop 0
	global_load_lds_dwordx4 v146, s[52:53]
	s_mov_b32 m0, s18
	s_nop 0
	global_load_lds_dwordx4 v144, s[52:53]
	s_waitcnt vmcnt(8)
	s_waitcnt lgkmcnt(0)
	s_barrier
; #define PG8_STAGE(bufoff, gbase, voff) do { _Pragma("unroll") for (int _i = 0; _i < 2; ++_i) \
;         __builtin_amdgcn_global_load_lds((const unsigned*)((const char*)(gbase) + (voff)[_i]), (LAS unsigned*)(lds + (bufoff) + ldsw + _i * 8192), 16, 0, 0); } while (0)
; #define PG8_LDA(dst, b, h) do { _Pragma("unroll") for (int m = 0; m < 4; ++m) _Pragma("unroll") for (int k = 0; k < 2; ++k) dst[m][k] = *(const LAS bf16x8*)(lds + PG8_SA(b, h) + aoff + m * 2048 + k * 1024); } while (0)
; #define PG8_LDB(dst, b, h) do { _Pragma("unroll") for (int n = 0; n < 2; ++n) _Pragma("unroll") for (int k = 0; k < 2; ++k) dst[n][k] = *(const LAS bf16x8*)(lds + PG8_SB(b, h) + boff + n * 2048 + k * 1024); } while (0)
; #define PG8_MMA(ai, bj, At, Bt) do { __builtin_amdgcn_s_setprio(1); _Pragma("unroll") for (int m = 0; m < 4; ++m) _Pragma("unroll") for (int n = 0; n < 2; ++n) _Pragma("unroll") for (int k = 0; k < 2; ++k) \
;         acc[ai][bj][m][n] = __builtin_amdgcn_mfma_f32_16x16x32_bf16(Bt[n][k], At[m][k], acc[ai][bj][m][n], 0, 0, 0); __builtin_amdgcn_s_setprio(0); } while (0)
; #define PG8_WAIT_V(n) asm volatile("s_waitcnt vmcnt(" #n ")" ::: "memory")
; #define PG8_WAIT_L(n) asm volatile("s_waitcnt lgkmcnt(" #n ")" ::: "memory")
; #define PG8_BAR __builtin_amdgcn_s_barrier()
; #define PG8_SCHED __builtin_amdgcn_sched_barrier(0)
; template <class Epi, class Sched>
; __device__ __forceinline__ void gemm_phase(LAS unsigned char* lds, const Gemm g, const Sched& S, const Epi& E) {
;     ...
;             PG8_WAIT_V(8); PG8_WAIT_L(0); PG8_BAR; PG8_MMA(1, 0, At, B0); PG8_MMA(1, 1, At, B1); PG8_BAR; PG8_SCHED;
;             PG8_LDB(B0, 1, 0); PG8_LDB(B1, 1, 1); PG8_SCHED; PG8_LDA(At, 1, 0); PG8_STAGE(PG8_SA(0, 1), a2 + hstep, voffA);
;             PG8_WAIT_V(8); PG8_WAIT_L(0); PG8_BAR; PG8_MMA(0, 0, At, B0); PG8_MMA(0, 1, At, B1); PG8_BAR; PG8_SCHED;
	s_setprio 1
	v_mfma_f32_16x16x32_bf16 v[62:65], v[130:133], v[178:181], v[62:65]
	v_mfma_f32_16x16x32_bf16 v[58:61], v[138:141], v[178:181], v[58:61]
	v_mfma_f32_16x16x32_bf16 v[46:49], v[130:133], v[192:195], v[46:49]
	v_mfma_f32_16x16x32_bf16 v[42:45], v[138:141], v[192:195], v[42:45]
	v_mfma_f32_16x16x32_bf16 v[30:33], v[130:133], v[200:203], v[30:33]
	v_mfma_f32_16x16x32_bf16 v[26:29], v[138:141], v[200:203], v[26:29]
	v_mfma_f32_16x16x32_bf16 v[14:17], v[130:133], v[208:211], v[14:17]
	v_mfma_f32_16x16x32_bf16 v[10:13], v[138:141], v[208:211], v[10:13]
	v_mfma_f32_16x16x32_bf16 v[62:65], v[134:137], v[182:185], v[62:65]
	v_mfma_f32_16x16x32_bf16 v[58:61], v[154:157], v[182:185], v[58:61]
	v_mfma_f32_16x16x32_bf16 v[46:49], v[134:137], v[196:199], v[46:49]
	v_mfma_f32_16x16x32_bf16 v[42:45], v[154:157], v[196:199], v[42:45]
	v_mfma_f32_16x16x32_bf16 v[30:33], v[134:137], v[204:207], v[30:33]
	v_mfma_f32_16x16x32_bf16 v[26:29], v[154:157], v[204:207], v[26:29]
	v_mfma_f32_16x16x32_bf16 v[14:17], v[134:137], v[212:215], v[14:17]
	v_mfma_f32_16x16x32_bf16 v[10:13], v[154:157], v[212:215], v[10:13]
	v_mfma_f32_16x16x32_bf16 v[54:57], v[162:165], v[178:181], v[54:57]
	v_mfma_f32_16x16x32_bf16 v[50:53], v[170:173], v[178:181], v[50:53]
	v_mfma_f32_16x16x32_bf16 v[38:41], v[162:165], v[192:195], v[38:41]
	v_mfma_f32_16x16x32_bf16 v[34:37], v[170:173], v[192:195], v[34:37]
	v_mfma_f32_16x16x32_bf16 v[22:25], v[162:165], v[200:203], v[22:25]
	v_mfma_f32_16x16x32_bf16 v[18:21], v[170:173], v[200:203], v[18:21]
	v_mfma_f32_16x16x32_bf16 v[6:9], v[162:165], v[208:211], v[6:9]
	v_mfma_f32_16x16x32_bf16 v[2:5], v[170:173], v[208:211], v[2:5]
	v_mfma_f32_16x16x32_bf16 v[54:57], v[166:169], v[182:185], v[54:57]
	v_mfma_f32_16x16x32_bf16 v[50:53], v[174:177], v[182:185], v[50:53]
	v_mfma_f32_16x16x32_bf16 v[38:41], v[166:169], v[196:199], v[38:41]
	v_mfma_f32_16x16x32_bf16 v[34:37], v[174:177], v[196:199], v[34:37]
	v_mfma_f32_16x16x32_bf16 v[22:25], v[166:169], v[204:207], v[22:25]
	v_mfma_f32_16x16x32_bf16 v[18:21], v[174:177], v[204:207], v[18:21]
	v_mfma_f32_16x16x32_bf16 v[6:9], v[166:169], v[212:215], v[6:9]
	v_mfma_f32_16x16x32_bf16 v[2:5], v[174:177], v[212:215], v[2:5]
	s_setprio 0
	s_barrier
	s_add_i32 s1, 0, 0x18000
	s_add_i32 s59, 0, 0x1c000
	v_add_u32_e32 v154, s1, v160
	v_add_u32_e32 v174, s59, v160
	ds_read_b128 v[130:133], v154
	ds_read_b128 v[134:137], v154 offset:1024
	ds_read_b128 v[138:141], v154 offset:2048
	ds_read_b128 v[154:157], v154 offset:3072
	ds_read_b128 v[162:165], v174
	ds_read_b128 v[166:169], v174 offset:1024
	ds_read_b128 v[170:173], v174 offset:2048
	ds_read_b128 v[174:177], v174 offset:3072
	s_add_u32 s48, s52, s26
	s_addc_u32 s49, s53, s27
	s_mov_b32 m0, s19
	ds_read_b128 v[178:181], v161 offset:32768
	ds_read_b128 v[182:185], v161 offset:33792
	ds_read_b128 v[192:195], v161 offset:34816
	ds_read_b128 v[196:199], v161 offset:35840
	ds_read_b128 v[200:203], v161 offset:36864
	ds_read_b128 v[204:207], v161 offset:37888
	ds_read_b128 v[208:211], v161 offset:38912
	ds_read_b128 v[212:215], v161 offset:39936
	global_load_lds_dwordx4 v146, s[48:49]
	s_mov_b32 m0, s20
	s_nop 0
	global_load_lds_dwordx4 v144, s[48:49]
	s_waitcnt vmcnt(8)
	s_waitcnt lgkmcnt(0)
	s_barrier
	s_setprio 1
	v_mfma_f32_16x16x32_bf16 v[122:125], v[130:133], v[178:181], v[122:125]
	v_mfma_f32_16x16x32_bf16 v[126:129], v[138:141], v[178:181], v[126:129]
	v_mfma_f32_16x16x32_bf16 v[110:113], v[130:133], v[192:195], v[110:113]
	v_mfma_f32_16x16x32_bf16 v[106:109], v[138:141], v[192:195], v[106:109]
	v_mfma_f32_16x16x32_bf16 v[94:97], v[130:133], v[200:203], v[94:97]
	v_mfma_f32_16x16x32_bf16 v[90:93], v[138:141], v[200:203], v[90:93]
	v_mfma_f32_16x16x32_bf16 v[78:81], v[130:133], v[208:211], v[78:81]
	v_mfma_f32_16x16x32_bf16 v[74:77], v[138:141], v[208:211], v[74:77]
	v_mfma_f32_16x16x32_bf16 v[122:125], v[134:137], v[182:185], v[122:125]
	v_mfma_f32_16x16x32_bf16 v[126:129], v[154:157], v[182:185], v[126:129]
	v_mfma_f32_16x16x32_bf16 v[110:113], v[134:137], v[196:199], v[110:113]
	v_mfma_f32_16x16x32_bf16 v[106:109], v[154:157], v[196:199], v[106:109]
	v_mfma_f32_16x16x32_bf16 v[94:97], v[134:137], v[204:207], v[94:97]
	v_mfma_f32_16x16x32_bf16 v[90:93], v[154:157], v[204:207], v[90:93]
	v_mfma_f32_16x16x32_bf16 v[78:81], v[134:137], v[212:215], v[78:81]
	v_mfma_f32_16x16x32_bf16 v[74:77], v[154:157], v[212:215], v[74:77]
	v_mfma_f32_16x16x32_bf16 v[118:121], v[162:165], v[178:181], v[118:121]
	v_mfma_f32_16x16x32_bf16 v[114:117], v[170:173], v[178:181], v[114:117]
	v_mfma_f32_16x16x32_bf16 v[102:105], v[162:165], v[192:195], v[102:105]
	v_mfma_f32_16x16x32_bf16 v[98:101], v[170:173], v[192:195], v[98:101]
	v_mfma_f32_16x16x32_bf16 v[86:89], v[162:165], v[200:203], v[86:89]
	v_mfma_f32_16x16x32_bf16 v[82:85], v[170:173], v[200:203], v[82:85]
	v_mfma_f32_16x16x32_bf16 v[70:73], v[162:165], v[208:211], v[70:73]
	v_mfma_f32_16x16x32_bf16 v[66:69], v[170:173], v[208:211], v[66:69]
	v_mfma_f32_16x16x32_bf16 v[118:121], v[166:169], v[182:185], v[118:121]
	v_mfma_f32_16x16x32_bf16 v[114:117], v[174:177], v[182:185], v[114:117]
	v_mfma_f32_16x16x32_bf16 v[102:105], v[166:169], v[196:199], v[102:105]
	v_mfma_f32_16x16x32_bf16 v[98:101], v[174:177], v[196:199], v[98:101]
	v_mfma_f32_16x16x32_bf16 v[86:89], v[166:169], v[204:207], v[86:89]
	v_mfma_f32_16x16x32_bf16 v[82:85], v[174:177], v[204:207], v[82:85]
	v_mfma_f32_16x16x32_bf16 v[70:73], v[166:169], v[212:215], v[70:73]
	v_mfma_f32_16x16x32_bf16 v[66:69], v[174:177], v[212:215], v[66:69]
	s_setprio 0
	s_barrier
; #define PG8_STAGE(bufoff, gbase, voff) do { _Pragma("unroll") for (int _i = 0; _i < 2; ++_i) \
;         __builtin_amdgcn_global_load_lds((const unsigned*)((const char*)(gbase) + (voff)[_i]), (LAS unsigned*)(lds + (bufoff) + ldsw + _i * 8192), 16, 0, 0); } while (0)
; #define PG8_LDA(dst, b, h) do { _Pragma("unroll") for (int m = 0; m < 4; ++m) _Pragma("unroll") for (int k = 0; k < 2; ++k) dst[m][k] = *(const LAS bf16x8*)(lds + PG8_SA(b, h) + aoff + m * 2048 + k * 1024); } while (0)
; #define PG8_MMA(ai, bj, At, Bt) do { __builtin_amdgcn_s_setprio(1); _Pragma("unroll") for (int m = 0; m < 4; ++m) _Pragma("unroll") for (int n = 0; n < 2; ++n) _Pragma("unroll") for (int k = 0; k < 2; ++k) \
;         acc[ai][bj][m][n] = __builtin_amdgcn_mfma_f32_16x16x32_bf16(Bt[n][k], At[m][k], acc[ai][bj][m][n], 0, 0, 0); __builtin_amdgcn_s_setprio(0); } while (0)
; #define PG8_WAIT_V(n) asm volatile("s_waitcnt vmcnt(" #n ")" ::: "memory")
; #define PG8_WAIT_L(n) asm volatile("s_waitcnt lgkmcnt(" #n ")" ::: "memory")
; #define PG8_BAR __builtin_amdgcn_s_barrier()
; #define PG8_SCHED __builtin_amdgcn_sched_barrier(0)
; template <class Epi, class Sched>
; __device__ __forceinline__ void gemm_phase(LAS unsigned char* lds, const Gemm g, const Sched& S, const Epi& E) {
;     ...
;             PG8_LDA(At, 1, 1); PG8_STAGE(PG8_SB(1, 0), b3, voffB); PG8_STAGE(PG8_SB(1, 1), b3 + hstep, voffB); PG8_STAGE(PG8_SA(1, 0), a3, voffA);
;             PG8_WAIT_V(8); PG8_WAIT_L(0); PG8_BAR; PG8_MMA(1, 0, At, B0); PG8_MMA(1, 1, At, B1); PG8_BAR; PG8_SCHED;
;         }
	s_add_i32 s1, s1, s4
	s_add_u32 s48, s60, 0x80
	s_addc_u32 s49, s61, 0
	s_mov_b32 m0, s1
	ds_read_b128 v[178:181], v161 offset:49152
	ds_read_b128 v[182:185], v161 offset:50176
	ds_read_b128 v[192:195], v161 offset:51200
	ds_read_b128 v[196:199], v161 offset:52224
	ds_read_b128 v[200:203], v161 offset:53248
	ds_read_b128 v[204:207], v161 offset:54272
	ds_read_b128 v[208:211], v161 offset:55296
	ds_read_b128 v[212:215], v161 offset:56320
	global_load_lds_dwordx4 v0, s[48:49]
	s_add_i32 m0, s1, 0x2000
	s_add_i32 s1, s59, s4
	global_load_lds_dwordx4 v142, s[48:49]
	s_add_u32 s48, s48, s26
	s_addc_u32 s49, s49, s27
	s_mov_b32 m0, s1
	s_nop 0
	global_load_lds_dwordx4 v0, s[48:49]
	s_add_i32 m0, s1, 0x2000
	s_nop 0
	global_load_lds_dwordx4 v142, s[48:49]
	s_add_u32 s48, s52, 0x80
	s_addc_u32 s49, s53, 0
	s_mov_b32 m0, s54
	s_nop 0
	global_load_lds_dwordx4 v146, s[48:49]
	s_mov_b32 m0, s55
	s_nop 0
	global_load_lds_dwordx4 v144, s[48:49]
	s_waitcnt vmcnt(8)
	s_waitcnt lgkmcnt(0)
	s_barrier
	s_setprio 1
	v_mfma_f32_16x16x32_bf16 v[62:65], v[130:133], v[178:181], v[62:65]
	v_mfma_f32_16x16x32_bf16 v[58:61], v[138:141], v[178:181], v[58:61]
	v_mfma_f32_16x16x32_bf16 v[46:49], v[130:133], v[192:195], v[46:49]
	v_mfma_f32_16x16x32_bf16 v[42:45], v[138:141], v[192:195], v[42:45]
	v_mfma_f32_16x16x32_bf16 v[30:33], v[130:133], v[200:203], v[30:33]
	v_mfma_f32_16x16x32_bf16 v[26:29], v[138:141], v[200:203], v[26:29]
	v_mfma_f32_16x16x32_bf16 v[14:17], v[130:133], v[208:211], v[14:17]
	v_mfma_f32_16x16x32_bf16 v[10:13], v[138:141], v[208:211], v[10:13]
	v_mfma_f32_16x16x32_bf16 v[62:65], v[134:137], v[182:185], v[62:65]
	v_mfma_f32_16x16x32_bf16 v[58:61], v[154:157], v[182:185], v[58:61]
	v_mfma_f32_16x16x32_bf16 v[46:49], v[134:137], v[196:199], v[46:49]
	v_mfma_f32_16x16x32_bf16 v[42:45], v[154:157], v[196:199], v[42:45]
	v_mfma_f32_16x16x32_bf16 v[30:33], v[134:137], v[204:207], v[30:33]
	v_mfma_f32_16x16x32_bf16 v[26:29], v[154:157], v[204:207], v[26:29]
	v_mfma_f32_16x16x32_bf16 v[14:17], v[134:137], v[212:215], v[14:17]
	v_mfma_f32_16x16x32_bf16 v[10:13], v[154:157], v[212:215], v[10:13]
	v_mfma_f32_16x16x32_bf16 v[54:57], v[162:165], v[178:181], v[54:57]
	v_mfma_f32_16x16x32_bf16 v[50:53], v[170:173], v[178:181], v[50:53]
	v_mfma_f32_16x16x32_bf16 v[38:41], v[162:165], v[192:195], v[38:41]
	v_mfma_f32_16x16x32_bf16 v[34:37], v[170:173], v[192:195], v[34:37]
	v_mfma_f32_16x16x32_bf16 v[22:25], v[162:165], v[200:203], v[22:25]
	v_mfma_f32_16x16x32_bf16 v[18:21], v[170:173], v[200:203], v[18:21]
	v_mfma_f32_16x16x32_bf16 v[6:9], v[162:165], v[208:211], v[6:9]
	v_mfma_f32_16x16x32_bf16 v[2:5], v[170:173], v[208:211], v[2:5]
	v_mfma_f32_16x16x32_bf16 v[54:57], v[166:169], v[182:185], v[54:57]
	v_mfma_f32_16x16x32_bf16 v[50:53], v[174:177], v[182:185], v[50:53]
	v_mfma_f32_16x16x32_bf16 v[38:41], v[166:169], v[196:199], v[38:41]
	v_mfma_f32_16x16x32_bf16 v[34:37], v[174:177], v[196:199], v[34:37]
	v_mfma_f32_16x16x32_bf16 v[22:25], v[166:169], v[204:207], v[22:25]
	v_mfma_f32_16x16x32_bf16 v[18:21], v[174:177], v[204:207], v[18:21]
	v_mfma_f32_16x16x32_bf16 v[6:9], v[166:169], v[212:215], v[6:9]
	v_mfma_f32_16x16x32_bf16 v[2:5], v[174:177], v[212:215], v[2:5]
	s_setprio 0
	s_barrier
	s_cmp_ge_i32 s58, s21
	s_mov_b64 s[48:49], s[50:51]
	s_mov_b32 s52, s58
	s_cbranch_scc0 .LBB0_418

; #define PG8_STAGE(bufoff, gbase, voff) do { _Pragma("unroll") for (int _i = 0; _i < 2; ++_i) \
;         __builtin_amdgcn_global_load_lds((const unsigned*)((const char*)(gbase) + (voff)[_i]), (LAS unsigned*)(lds + (bufoff) + ldsw + _i * 8192), 16, 0, 0); } while (0)
; #define PG8_LDA(dst, b, h) do { _Pragma("unroll") for (int m = 0; m < 4; ++m) _Pragma("unroll") for (int k = 0; k < 2; ++k) dst[m][k] = *(const LAS bf16x8*)(lds + PG8_SA(b, h) + aoff + m * 2048 + k * 1024); } while (0)
; #define PG8_LDB(dst, b, h) do { _Pragma("unroll") for (int n = 0; n < 2; ++n) _Pragma("unroll") for (int k = 0; k < 2; ++k) dst[n][k] = *(const LAS bf16x8*)(lds + PG8_SB(b, h) + boff + n * 2048 + k * 1024); } while (0)
; #define PG8_MMA(ai, bj, At, Bt) do { __builtin_amdgcn_s_setprio(1); _Pragma("unroll") for (int m = 0; m < 4; ++m) _Pragma("unroll") for (int n = 0; n < 2; ++n) _Pragma("unroll") for (int k = 0; k < 2; ++k) \
;         acc[ai][bj][m][n] = __builtin_amdgcn_mfma_f32_16x16x32_bf16(Bt[n][k], At[m][k], acc[ai][bj][m][n], 0, 0, 0); __builtin_amdgcn_s_setprio(0); } while (0)
; #define PG8_WAIT_V(n) asm volatile("s_waitcnt vmcnt(" #n ")" ::: "memory")
; #define PG8_WAIT_L(n) asm volatile("s_waitcnt lgkmcnt(" #n ")" ::: "memory")
; #define PG8_BAR __builtin_amdgcn_s_barrier()
; template <class Epi, class Sched>
; __device__ __forceinline__ void gemm_phase(LAS unsigned char* lds, const Gemm g, const Sched& S, const Epi& E) {
;     ...
;         for (int t = 0; t < nt; t += 2) {
;             const bool last = (t == nt - 2);
;             const char* a1 = cA + (size_t)(t + 1) * kstep;
;             const char* a2 = last ? nA : cA + (size_t)(t + 2) * kstep; const char* b2 = last ? nB : cB + (size_t)(t + 2) * kstep;
;             const char* a3 = a2 + kstep; const char* b3 = b2 + kstep;
;             if (last && has_next) S.a_ready(nxt);
;             PG8_LDB(B0, 0, 0); PG8_LDB(B1, 0, 1); PG8_SCHED; PG8_LDA(At, 0, 0); PG8_STAGE(PG8_SA(1, 1), a1 + hstep, voffA);
;             PG8_WAIT_V(8); PG8_WAIT_L(0); PG8_BAR; PG8_MMA(0, 0, At, B0); PG8_MMA(0, 1, At, B1); PG8_BAR; PG8_SCHED;
;             PG8_LDA(At, 0, 1); PG8_STAGE(PG8_SB(0, 0), b2, voffB); PG8_STAGE(PG8_SB(0, 1), b2 + hstep, voffB); PG8_STAGE(PG8_SA(0, 0), a2, voffA);
;             PG8_WAIT_V(8); PG8_WAIT_L(0); PG8_BAR; PG8_MMA(1, 0, At, B0); PG8_MMA(1, 1, At, B1); PG8_BAR; PG8_SCHED;
.LBB0_435:
	s_add_i32 s62, s52, 2
	s_add_u32 s50, s48, 0x100
	s_addc_u32 s51, s49, 0
	s_add_u32 s1, s9, s48
	s_addc_u32 s53, s36, s49
	s_cmp_eq_u32 s60, s52
	s_cselect_b32 s52, s100, s50
	s_cselect_b32 s63, 0, s51
	s_cselect_b32 s64, s46, s1
	s_cselect_b32 s65, s47, s53
	s_add_u32 s52, s2, s52
	s_addc_u32 s53, s3, s63
	s_add_i32 s1, 0, 0x10000
	s_add_i32 s63, 0, 0x14000
	v_add_u32_e32 v156, s1, v142
	v_add_u32_e32 v172, s63, v142
	ds_read_b128 v[144:147], v156
	ds_read_b128 v[148:151], v156 offset:1024
	ds_read_b128 v[152:155], v156 offset:2048
	ds_read_b128 v[156:159], v156 offset:3072
	ds_read_b128 v[160:163], v172
	ds_read_b128 v[164:167], v172 offset:1024
	ds_read_b128 v[168:171], v172 offset:2048
	ds_read_b128 v[172:175], v172 offset:3072
	s_add_u32 s48, s48, s2
	s_addc_u32 s49, s49, s3
	s_add_u32 s48, s48, s26
	s_addc_u32 s49, s49, s27
	s_add_u32 s48, s48, 0x80
	s_addc_u32 s49, s49, 0
	s_add_i32 m0, s5, 0xc000
	ds_read_b128 v[176:179], v143
	ds_read_b128 v[180:183], v143 offset:1024
	ds_read_b128 v[184:187], v143 offset:2048
	ds_read_b128 v[192:195], v143 offset:3072
	ds_read_b128 v[196:199], v143 offset:4096
	ds_read_b128 v[200:203], v143 offset:5120
	ds_read_b128 v[204:207], v143 offset:6144
	ds_read_b128 v[208:211], v143 offset:7168
	global_load_lds_dwordx4 v134, s[48:49]
	s_add_i32 m0, s5, 0xe000
	s_nop 0
	global_load_lds_dwordx4 v132, s[48:49]
	s_waitcnt vmcnt(8)
	s_waitcnt lgkmcnt(0)
	s_barrier
	s_setprio 1
	v_mfma_f32_16x16x32_bf16 v[122:125], v[144:147], v[176:179], v[122:125]
	v_mfma_f32_16x16x32_bf16 v[126:129], v[152:155], v[176:179], v[126:129]
	v_mfma_f32_16x16x32_bf16 v[110:113], v[144:147], v[184:187], v[110:113]
	v_mfma_f32_16x16x32_bf16 v[106:109], v[152:155], v[184:187], v[106:109]
	v_mfma_f32_16x16x32_bf16 v[94:97], v[144:147], v[196:199], v[94:97]
	v_mfma_f32_16x16x32_bf16 v[90:93], v[152:155], v[196:199], v[90:93]
	v_mfma_f32_16x16x32_bf16 v[78:81], v[144:147], v[204:207], v[78:81]
	v_mfma_f32_16x16x32_bf16 v[74:77], v[152:155], v[204:207], v[74:77]
	v_mfma_f32_16x16x32_bf16 v[122:125], v[148:151], v[180:183], v[122:125]
	v_mfma_f32_16x16x32_bf16 v[126:129], v[156:159], v[180:183], v[126:129]
	v_mfma_f32_16x16x32_bf16 v[110:113], v[148:151], v[192:195], v[110:113]
	v_mfma_f32_16x16x32_bf16 v[106:109], v[156:159], v[192:195], v[106:109]
	v_mfma_f32_16x16x32_bf16 v[94:97], v[148:151], v[200:203], v[94:97]
	v_mfma_f32_16x16x32_bf16 v[90:93], v[156:159], v[200:203], v[90:93]
	v_mfma_f32_16x16x32_bf16 v[78:81], v[148:151], v[208:211], v[78:81]
	v_mfma_f32_16x16x32_bf16 v[74:77], v[156:159], v[208:211], v[74:77]
	v_mfma_f32_16x16x32_bf16 v[118:121], v[160:163], v[176:179], v[118:121]
	v_mfma_f32_16x16x32_bf16 v[114:117], v[168:171], v[176:179], v[114:117]
	v_mfma_f32_16x16x32_bf16 v[102:105], v[160:163], v[184:187], v[102:105]
	v_mfma_f32_16x16x32_bf16 v[98:101], v[168:171], v[184:187], v[98:101]
	v_mfma_f32_16x16x32_bf16 v[86:89], v[160:163], v[196:199], v[86:89]
	v_mfma_f32_16x16x32_bf16 v[82:85], v[168:171], v[196:199], v[82:85]
	v_mfma_f32_16x16x32_bf16 v[70:73], v[160:163], v[204:207], v[70:73]
	v_mfma_f32_16x16x32_bf16 v[66:69], v[168:171], v[204:207], v[66:69]
	v_mfma_f32_16x16x32_bf16 v[118:121], v[164:167], v[180:183], v[118:121]
	v_mfma_f32_16x16x32_bf16 v[114:117], v[172:175], v[180:183], v[114:117]
	v_mfma_f32_16x16x32_bf16 v[102:105], v[164:167], v[192:195], v[102:105]
	v_mfma_f32_16x16x32_bf16 v[98:101], v[172:175], v[192:195], v[98:101]
	v_mfma_f32_16x16x32_bf16 v[86:89], v[164:167], v[200:203], v[86:89]
	v_mfma_f32_16x16x32_bf16 v[82:85], v[172:175], v[200:203], v[82:85]
	v_mfma_f32_16x16x32_bf16 v[70:73], v[164:167], v[208:211], v[70:73]
	v_mfma_f32_16x16x32_bf16 v[66:69], v[172:175], v[208:211], v[66:69]
	s_setprio 0
	s_barrier
	s_add_i32 s1, s1, s4
	s_mov_b32 m0, s1
	ds_read_b128 v[176:179], v143 offset:16384
	ds_read_b128 v[180:183], v143 offset:17408
	ds_read_b128 v[184:187], v143 offset:18432
	ds_read_b128 v[192:195], v143 offset:19456
	ds_read_b128 v[196:199], v143 offset:20480
	ds_read_b128 v[200:203], v143 offset:21504
	ds_read_b128 v[204:207], v143 offset:22528
	ds_read_b128 v[208:211], v143 offset:23552
	global_load_lds_dwordx4 v0, s[64:65]
	s_add_i32 m0, s1, 0x2000
	s_add_u32 s48, s64, s26
	s_addc_u32 s49, s65, s27
	s_add_i32 s1, s63, s4
	global_load_lds_dwordx4 v130, s[64:65]
	s_mov_b32 m0, s1
	s_nop 0
	global_load_lds_dwordx4 v0, s[48:49]
	s_add_i32 m0, s1, 0x2000
	s_nop 0
	global_load_lds_dwordx4 v130, s[48:49]
	s_mov_b32 m0, s5
	s_nop 0
	global_load_lds_dwordx4 v134, s[52:53]
	s_mov_b32 m0, s54
	s_nop 0
	global_load_lds_dwordx4 v132, s[52:53]
	s_waitcnt vmcnt(8)
	s_waitcnt lgkmcnt(0)
	s_barrier
; #define PG8_STAGE(bufoff, gbase, voff) do { _Pragma("unroll") for (int _i = 0; _i < 2; ++_i) \
;         __builtin_amdgcn_global_load_lds((const unsigned*)((const char*)(gbase) + (voff)[_i]), (LAS unsigned*)(lds + (bufoff) + ldsw + _i * 8192), 16, 0, 0); } while (0)
; #define PG8_LDA(dst, b, h) do { _Pragma("unroll") for (int m = 0; m < 4; ++m) _Pragma("unroll") for (int k = 0; k < 2; ++k) dst[m][k] = *(const LAS bf16x8*)(lds + PG8_SA(b, h) + aoff + m * 2048 + k * 1024); } while (0)
; #define PG8_LDB(dst, b, h) do { _Pragma("unroll") for (int n = 0; n < 2; ++n) _Pragma("unroll") for (int k = 0; k < 2; ++k) dst[n][k] = *(const LAS bf16x8*)(lds + PG8_SB(b, h) + boff + n * 2048 + k * 1024); } while (0)
; #define PG8_MMA(ai, bj, At, Bt) do { __builtin_amdgcn_s_setprio(1); _Pragma("unroll") for (int m = 0; m < 4; ++m) _Pragma("unroll") for (int n = 0; n < 2; ++n) _Pragma("unroll") for (int k = 0; k < 2; ++k) \
;         acc[ai][bj][m][n] = __builtin_amdgcn_mfma_f32_16x16x32_bf16(Bt[n][k], At[m][k], acc[ai][bj][m][n], 0, 0, 0); __builtin_amdgcn_s_setprio(0); } while (0)
; #define PG8_WAIT_V(n) asm volatile("s_waitcnt vmcnt(" #n ")" ::: "memory")
; #define PG8_WAIT_L(n) asm volatile("s_waitcnt lgkmcnt(" #n ")" ::: "memory")
; #define PG8_BAR __builtin_amdgcn_s_barrier()
; #define PG8_SCHED __builtin_amdgcn_sched_barrier(0)
; template <class Epi, class Sched>
; __device__ __forceinline__ void gemm_phase(LAS unsigned char* lds, const Gemm g, const Sched& S, const Epi& E) {
;     ...
;             PG8_WAIT_V(8); PG8_WAIT_L(0); PG8_BAR; PG8_MMA(1, 0, At, B0); PG8_MMA(1, 1, At, B1); PG8_BAR; PG8_SCHED;
;             PG8_LDB(B0, 1, 0); PG8_LDB(B1, 1, 1); PG8_SCHED; PG8_LDA(At, 1, 0); PG8_STAGE(PG8_SA(0, 1), a2 + hstep, voffA);
;             PG8_WAIT_V(8); PG8_WAIT_L(0); PG8_BAR; PG8_MMA(0, 0, At, B0); PG8_MMA(0, 1, At, B1); PG8_BAR; PG8_SCHED;
	s_setprio 1
	v_mfma_f32_16x16x32_bf16 v[62:65], v[144:147], v[176:179], v[62:65]
	v_mfma_f32_16x16x32_bf16 v[58:61], v[152:155], v[176:179], v[58:61]
	v_mfma_f32_16x16x32_bf16 v[46:49], v[144:147], v[184:187], v[46:49]
	v_mfma_f32_16x16x32_bf16 v[42:45], v[152:155], v[184:187], v[42:45]
	v_mfma_f32_16x16x32_bf16 v[30:33], v[144:147], v[196:199], v[30:33]
	v_mfma_f32_16x16x32_bf16 v[26:29], v[152:155], v[196:199], v[26:29]
	v_mfma_f32_16x16x32_bf16 v[14:17], v[144:147], v[204:207], v[14:17]
	v_mfma_f32_16x16x32_bf16 v[10:13], v[152:155], v[204:207], v[10:13]
	v_mfma_f32_16x16x32_bf16 v[62:65], v[148:151], v[180:183], v[62:65]
	v_mfma_f32_16x16x32_bf16 v[58:61], v[156:159], v[180:183], v[58:61]
	v_mfma_f32_16x16x32_bf16 v[46:49], v[148:151], v[192:195], v[46:49]
	v_mfma_f32_16x16x32_bf16 v[42:45], v[156:159], v[192:195], v[42:45]
	v_mfma_f32_16x16x32_bf16 v[30:33], v[148:151], v[200:203], v[30:33]
	v_mfma_f32_16x16x32_bf16 v[26:29], v[156:159], v[200:203], v[26:29]
	v_mfma_f32_16x16x32_bf16 v[14:17], v[148:151], v[208:211], v[14:17]
	v_mfma_f32_16x16x32_bf16 v[10:13], v[156:159], v[208:211], v[10:13]
	v_mfma_f32_16x16x32_bf16 v[54:57], v[160:163], v[176:179], v[54:57]
	v_mfma_f32_16x16x32_bf16 v[50:53], v[168:171], v[176:179], v[50:53]
	v_mfma_f32_16x16x32_bf16 v[38:41], v[160:163], v[184:187], v[38:41]
	v_mfma_f32_16x16x32_bf16 v[34:37], v[168:171], v[184:187], v[34:37]
	v_mfma_f32_16x16x32_bf16 v[22:25], v[160:163], v[196:199], v[22:25]
	v_mfma_f32_16x16x32_bf16 v[18:21], v[168:171], v[196:199], v[18:21]
	v_mfma_f32_16x16x32_bf16 v[6:9], v[160:163], v[204:207], v[6:9]
	v_mfma_f32_16x16x32_bf16 v[2:5], v[168:171], v[204:207], v[2:5]
	v_mfma_f32_16x16x32_bf16 v[54:57], v[164:167], v[180:183], v[54:57]
	v_mfma_f32_16x16x32_bf16 v[50:53], v[172:175], v[180:183], v[50:53]
	v_mfma_f32_16x16x32_bf16 v[38:41], v[164:167], v[192:195], v[38:41]
	v_mfma_f32_16x16x32_bf16 v[34:37], v[172:175], v[192:195], v[34:37]
	v_mfma_f32_16x16x32_bf16 v[22:25], v[164:167], v[200:203], v[22:25]
	v_mfma_f32_16x16x32_bf16 v[18:21], v[172:175], v[200:203], v[18:21]
	v_mfma_f32_16x16x32_bf16 v[6:9], v[164:167], v[208:211], v[6:9]
	v_mfma_f32_16x16x32_bf16 v[2:5], v[172:175], v[208:211], v[2:5]
	s_setprio 0
	s_barrier
	s_add_i32 s1, 0, 0x18000
	s_add_i32 s63, 0, 0x1c000
	v_add_u32_e32 v156, s1, v142
	v_add_u32_e32 v172, s63, v142
	ds_read_b128 v[144:147], v156
	ds_read_b128 v[148:151], v156 offset:1024
	ds_read_b128 v[152:155], v156 offset:2048
	ds_read_b128 v[156:159], v156 offset:3072
	ds_read_b128 v[160:163], v172
	ds_read_b128 v[164:167], v172 offset:1024
	ds_read_b128 v[168:171], v172 offset:2048
	ds_read_b128 v[172:175], v172 offset:3072
	s_add_u32 s48, s52, s26
	s_addc_u32 s49, s53, s27
	s_mov_b32 m0, s55
	ds_read_b128 v[176:179], v143 offset:32768
	ds_read_b128 v[180:183], v143 offset:33792
	ds_read_b128 v[184:187], v143 offset:34816
	ds_read_b128 v[192:195], v143 offset:35840
	ds_read_b128 v[196:199], v143 offset:36864
	ds_read_b128 v[200:203], v143 offset:37888
	ds_read_b128 v[204:207], v143 offset:38912
	ds_read_b128 v[208:211], v143 offset:39936
	global_load_lds_dwordx4 v134, s[48:49]
	s_mov_b32 m0, s56
	s_nop 0
	global_load_lds_dwordx4 v132, s[48:49]
	s_waitcnt vmcnt(8)
	s_waitcnt lgkmcnt(0)
	s_barrier
	s_setprio 1
	v_mfma_f32_16x16x32_bf16 v[122:125], v[144:147], v[176:179], v[122:125]
	v_mfma_f32_16x16x32_bf16 v[126:129], v[152:155], v[176:179], v[126:129]
	v_mfma_f32_16x16x32_bf16 v[110:113], v[144:147], v[184:187], v[110:113]
	v_mfma_f32_16x16x32_bf16 v[106:109], v[152:155], v[184:187], v[106:109]
	v_mfma_f32_16x16x32_bf16 v[94:97], v[144:147], v[196:199], v[94:97]
	v_mfma_f32_16x16x32_bf16 v[90:93], v[152:155], v[196:199], v[90:93]
	v_mfma_f32_16x16x32_bf16 v[78:81], v[144:147], v[204:207], v[78:81]
	v_mfma_f32_16x16x32_bf16 v[74:77], v[152:155], v[204:207], v[74:77]
	v_mfma_f32_16x16x32_bf16 v[122:125], v[148:151], v[180:183], v[122:125]
	v_mfma_f32_16x16x32_bf16 v[126:129], v[156:159], v[180:183], v[126:129]
	v_mfma_f32_16x16x32_bf16 v[110:113], v[148:151], v[192:195], v[110:113]
	v_mfma_f32_16x16x32_bf16 v[106:109], v[156:159], v[192:195], v[106:109]
	v_mfma_f32_16x16x32_bf16 v[94:97], v[148:151], v[200:203], v[94:97]
	v_mfma_f32_16x16x32_bf16 v[90:93], v[156:159], v[200:203], v[90:93]
	v_mfma_f32_16x16x32_bf16 v[78:81], v[148:151], v[208:211], v[78:81]
	v_mfma_f32_16x16x32_bf16 v[74:77], v[156:159], v[208:211], v[74:77]
	v_mfma_f32_16x16x32_bf16 v[118:121], v[160:163], v[176:179], v[118:121]
	v_mfma_f32_16x16x32_bf16 v[114:117], v[168:171], v[176:179], v[114:117]
	v_mfma_f32_16x16x32_bf16 v[102:105], v[160:163], v[184:187], v[102:105]
	v_mfma_f32_16x16x32_bf16 v[98:101], v[168:171], v[184:187], v[98:101]
	v_mfma_f32_16x16x32_bf16 v[86:89], v[160:163], v[196:199], v[86:89]
	v_mfma_f32_16x16x32_bf16 v[82:85], v[168:171], v[196:199], v[82:85]
	v_mfma_f32_16x16x32_bf16 v[70:73], v[160:163], v[204:207], v[70:73]
	v_mfma_f32_16x16x32_bf16 v[66:69], v[168:171], v[204:207], v[66:69]
	v_mfma_f32_16x16x32_bf16 v[118:121], v[164:167], v[180:183], v[118:121]
	v_mfma_f32_16x16x32_bf16 v[114:117], v[172:175], v[180:183], v[114:117]
	v_mfma_f32_16x16x32_bf16 v[102:105], v[164:167], v[192:195], v[102:105]
	v_mfma_f32_16x16x32_bf16 v[98:101], v[172:175], v[192:195], v[98:101]
	v_mfma_f32_16x16x32_bf16 v[86:89], v[164:167], v[200:203], v[86:89]
	v_mfma_f32_16x16x32_bf16 v[82:85], v[172:175], v[200:203], v[82:85]
	v_mfma_f32_16x16x32_bf16 v[70:73], v[164:167], v[208:211], v[70:73]
	v_mfma_f32_16x16x32_bf16 v[66:69], v[172:175], v[208:211], v[66:69]
	s_setprio 0
	s_barrier
; #define PG8_STAGE(bufoff, gbase, voff) do { _Pragma("unroll") for (int _i = 0; _i < 2; ++_i) \
;         __builtin_amdgcn_global_load_lds((const unsigned*)((const char*)(gbase) + (voff)[_i]), (LAS unsigned*)(lds + (bufoff) + ldsw + _i * 8192), 16, 0, 0); } while (0)
; #define PG8_LDA(dst, b, h) do { _Pragma("unroll") for (int m = 0; m < 4; ++m) _Pragma("unroll") for (int k = 0; k < 2; ++k) dst[m][k] = *(const LAS bf16x8*)(lds + PG8_SA(b, h) + aoff + m * 2048 + k * 1024); } while (0)
; #define PG8_MMA(ai, bj, At, Bt) do { __builtin_amdgcn_s_setprio(1); _Pragma("unroll") for (int m = 0; m < 4; ++m) _Pragma("unroll") for (int n = 0; n < 2; ++n) _Pragma("unroll") for (int k = 0; k < 2; ++k) \
;         acc[ai][bj][m][n] = __builtin_amdgcn_mfma_f32_16x16x32_bf16(Bt[n][k], At[m][k], acc[ai][bj][m][n], 0, 0, 0); __builtin_amdgcn_s_setprio(0); } while (0)
; #define PG8_WAIT_V(n) asm volatile("s_waitcnt vmcnt(" #n ")" ::: "memory")
; #define PG8_WAIT_L(n) asm volatile("s_waitcnt lgkmcnt(" #n ")" ::: "memory")
; #define PG8_BAR __builtin_amdgcn_s_barrier()
; #define PG8_SCHED __builtin_amdgcn_sched_barrier(0)
; template <class Epi, class Sched>
; __device__ __forceinline__ void gemm_phase(LAS unsigned char* lds, const Gemm g, const Sched& S, const Epi& E) {
;     ...
;             PG8_LDA(At, 1, 1); PG8_STAGE(PG8_SB(1, 0), b3, voffB); PG8_STAGE(PG8_SB(1, 1), b3 + hstep, voffB); PG8_STAGE(PG8_SA(1, 0), a3, voffA);
;             PG8_WAIT_V(8); PG8_WAIT_L(0); PG8_BAR; PG8_MMA(1, 0, At, B0); PG8_MMA(1, 1, At, B1); PG8_BAR; PG8_SCHED;
;         }
	s_add_i32 s1, s1, s4
	s_add_u32 s48, s64, 0x80
	s_addc_u32 s49, s65, 0
	s_mov_b32 m0, s1
	ds_read_b128 v[176:179], v143 offset:49152
	ds_read_b128 v[180:183], v143 offset:50176
	ds_read_b128 v[184:187], v143 offset:51200
	ds_read_b128 v[192:195], v143 offset:52224
	ds_read_b128 v[196:199], v143 offset:53248
	ds_read_b128 v[200:203], v143 offset:54272
	ds_read_b128 v[204:207], v143 offset:55296
	ds_read_b128 v[208:211], v143 offset:56320
	global_load_lds_dwordx4 v0, s[48:49]
	s_add_i32 m0, s1, 0x2000
	s_add_i32 s1, s63, s4
	global_load_lds_dwordx4 v130, s[48:49]
	s_add_u32 s48, s48, s26
	s_addc_u32 s49, s49, s27
	s_mov_b32 m0, s1
	s_nop 0
	global_load_lds_dwordx4 v0, s[48:49]
	s_add_i32 m0, s1, 0x2000
	s_nop 0
	global_load_lds_dwordx4 v130, s[48:49]
	s_add_u32 s48, s52, 0x80
	s_addc_u32 s49, s53, 0
	s_mov_b32 m0, s57
	s_nop 0
	global_load_lds_dwordx4 v134, s[48:49]
	s_mov_b32 m0, s58
	s_nop 0
	global_load_lds_dwordx4 v132, s[48:49]
	s_waitcnt vmcnt(8)
	s_waitcnt lgkmcnt(0)
	s_barrier
	s_setprio 1
	v_mfma_f32_16x16x32_bf16 v[62:65], v[144:147], v[176:179], v[62:65]
	v_mfma_f32_16x16x32_bf16 v[58:61], v[152:155], v[176:179], v[58:61]
	v_mfma_f32_16x16x32_bf16 v[46:49], v[144:147], v[184:187], v[46:49]
	v_mfma_f32_16x16x32_bf16 v[42:45], v[152:155], v[184:187], v[42:45]
	v_mfma_f32_16x16x32_bf16 v[30:33], v[144:147], v[196:199], v[30:33]
	v_mfma_f32_16x16x32_bf16 v[26:29], v[152:155], v[196:199], v[26:29]
	v_mfma_f32_16x16x32_bf16 v[14:17], v[144:147], v[204:207], v[14:17]
	v_mfma_f32_16x16x32_bf16 v[10:13], v[152:155], v[204:207], v[10:13]
	v_mfma_f32_16x16x32_bf16 v[62:65], v[148:151], v[180:183], v[62:65]
	v_mfma_f32_16x16x32_bf16 v[58:61], v[156:159], v[180:183], v[58:61]
	v_mfma_f32_16x16x32_bf16 v[46:49], v[148:151], v[192:195], v[46:49]
	v_mfma_f32_16x16x32_bf16 v[42:45], v[156:159], v[192:195], v[42:45]
	v_mfma_f32_16x16x32_bf16 v[30:33], v[148:151], v[200:203], v[30:33]
	v_mfma_f32_16x16x32_bf16 v[26:29], v[156:159], v[200:203], v[26:29]
	v_mfma_f32_16x16x32_bf16 v[14:17], v[148:151], v[208:211], v[14:17]
	v_mfma_f32_16x16x32_bf16 v[10:13], v[156:159], v[208:211], v[10:13]
	v_mfma_f32_16x16x32_bf16 v[54:57], v[160:163], v[176:179], v[54:57]
	v_mfma_f32_16x16x32_bf16 v[50:53], v[168:171], v[176:179], v[50:53]
	v_mfma_f32_16x16x32_bf16 v[38:41], v[160:163], v[184:187], v[38:41]
	v_mfma_f32_16x16x32_bf16 v[34:37], v[168:171], v[184:187], v[34:37]
	v_mfma_f32_16x16x32_bf16 v[22:25], v[160:163], v[196:199], v[22:25]
	v_mfma_f32_16x16x32_bf16 v[18:21], v[168:171], v[196:199], v[18:21]
	v_mfma_f32_16x16x32_bf16 v[6:9], v[160:163], v[204:207], v[6:9]
	v_mfma_f32_16x16x32_bf16 v[2:5], v[168:171], v[204:207], v[2:5]
	v_mfma_f32_16x16x32_bf16 v[54:57], v[164:167], v[180:183], v[54:57]
	v_mfma_f32_16x16x32_bf16 v[50:53], v[172:175], v[180:183], v[50:53]
	v_mfma_f32_16x16x32_bf16 v[38:41], v[164:167], v[192:195], v[38:41]
	v_mfma_f32_16x16x32_bf16 v[34:37], v[172:175], v[192:195], v[34:37]
	v_mfma_f32_16x16x32_bf16 v[22:25], v[164:167], v[200:203], v[22:25]
	v_mfma_f32_16x16x32_bf16 v[18:21], v[172:175], v[200:203], v[18:21]
	v_mfma_f32_16x16x32_bf16 v[6:9], v[164:167], v[208:211], v[6:9]
	v_mfma_f32_16x16x32_bf16 v[2:5], v[172:175], v[208:211], v[2:5]
	s_setprio 0
	s_barrier
	s_cmp_ge_i32 s62, s59
	s_mov_b64 s[48:49], s[50:51]
	s_mov_b32 s52, s62
	s_cbranch_scc0 .LBB0_435

; #define PG8_STAGE(bufoff, gbase, voff) do { _Pragma("unroll") for (int _i = 0; _i < 2; ++_i) \
;         __builtin_amdgcn_global_load_lds((const unsigned*)((const char*)(gbase) + (voff)[_i]), (LAS unsigned*)(lds + (bufoff) + ldsw + _i * 8192), 16, 0, 0); } while (0)
; #define PG8_LDA(dst, b, h) do { _Pragma("unroll") for (int m = 0; m < 4; ++m) _Pragma("unroll") for (int k = 0; k < 2; ++k) dst[m][k] = *(const LAS bf16x8*)(lds + PG8_SA(b, h) + aoff + m * 2048 + k * 1024); } while (0)
; #define PG8_LDB(dst, b, h) do { _Pragma("unroll") for (int n = 0; n < 2; ++n) _Pragma("unroll") for (int k = 0; k < 2; ++k) dst[n][k] = *(const LAS bf16x8*)(lds + PG8_SB(b, h) + boff + n * 2048 + k * 1024); } while (0)
; #define PG8_MMA(ai, bj, At, Bt) do { __builtin_amdgcn_s_setprio(1); _Pragma("unroll") for (int m = 0; m < 4; ++m) _Pragma("unroll") for (int n = 0; n < 2; ++n) _Pragma("unroll") for (int k = 0; k < 2; ++k) \
;         acc[ai][bj][m][n] = __builtin_amdgcn_mfma_f32_16x16x32_bf16(Bt[n][k], At[m][k], acc[ai][bj][m][n], 0, 0, 0); __builtin_amdgcn_s_setprio(0); } while (0)
; #define PG8_WAIT_V(n) asm volatile("s_waitcnt vmcnt(" #n ")" ::: "memory")
; #define PG8_WAIT_L(n) asm volatile("s_waitcnt lgkmcnt(" #n ")" ::: "memory")
; #define PG8_BAR __builtin_amdgcn_s_barrier()
; template <class Epi, class Sched>
; __device__ __forceinline__ void gemm_phase(LAS unsigned char* lds, const Gemm g, const Sched& S, const Epi& E) {
;     ...
;         for (int t = 0; t < nt; t += 2) {
;             const bool last = (t == nt - 2);
;             const char* a1 = cA + (size_t)(t + 1) * kstep;
;             const char* a2 = last ? nA : cA + (size_t)(t + 2) * kstep; const char* b2 = last ? nB : cB + (size_t)(t + 2) * kstep;
;             const char* a3 = a2 + kstep; const char* b3 = b2 + kstep;
;             if (last && has_next) S.a_ready(nxt);
;             PG8_LDB(B0, 0, 0); PG8_LDB(B1, 0, 1); PG8_SCHED; PG8_LDA(At, 0, 0); PG8_STAGE(PG8_SA(1, 1), a1 + hstep, voffA);
;             PG8_WAIT_V(8); PG8_WAIT_L(0); PG8_BAR; PG8_MMA(0, 0, At, B0); PG8_MMA(0, 1, At, B1); PG8_BAR; PG8_SCHED;
;             PG8_LDA(At, 0, 1); PG8_STAGE(PG8_SB(0, 0), b2, voffB); PG8_STAGE(PG8_SB(0, 1), b2 + hstep, voffB); PG8_STAGE(PG8_SA(0, 0), a2, voffA);
;             PG8_WAIT_V(8); PG8_WAIT_L(0); PG8_BAR; PG8_MMA(1, 0, At, B0); PG8_MMA(1, 1, At, B1); PG8_BAR; PG8_SCHED;
.LBB0_450:
	s_add_i32 s60, s50, 2
	s_add_u32 s48, s46, 0x100
	s_addc_u32 s49, s47, 0
	s_add_u32 s1, s9, s46
	s_addc_u32 s51, s36, s47
	s_cmp_eq_u32 s58, s50
	s_cselect_b32 s50, 0xff000000, s48
	s_cselect_b32 s61, -1, s49
	s_cselect_b32 s62, s44, s1
	s_cselect_b32 s63, s45, s51
	s_add_u32 s50, s2, s50
	s_addc_u32 s51, s3, s61
	s_add_i32 s1, 0, 0x10000
	s_add_i32 s61, 0, 0x14000
	v_add_u32_e32 v154, s1, v160
	v_add_u32_e32 v158, s61, v160
	ds_read_b128 v[130:133], v154
	ds_read_b128 v[134:137], v154 offset:1024
	ds_read_b128 v[138:141], v154 offset:2048
	ds_read_b128 v[154:157], v154 offset:3072
	ds_read_b128 v[162:165], v158
	ds_read_b128 v[166:169], v158 offset:1024
	ds_read_b128 v[170:173], v158 offset:2048
	ds_read_b128 v[174:177], v158 offset:3072
	s_add_u32 s46, s46, s2
	s_addc_u32 s47, s47, s3
	s_add_u32 s46, s46, s18
	s_addc_u32 s47, s47, s19
	s_add_u32 s46, s46, 0x80
	s_addc_u32 s47, s47, 0
	s_add_i32 m0, s5, 0xc000
	ds_read_b128 v[178:181], v161
	ds_read_b128 v[182:185], v161 offset:1024
	ds_read_b128 v[192:195], v161 offset:2048
	ds_read_b128 v[196:199], v161 offset:3072
	ds_read_b128 v[200:203], v161 offset:4096
	ds_read_b128 v[204:207], v161 offset:5120
	ds_read_b128 v[208:211], v161 offset:6144
	ds_read_b128 v[212:215], v161 offset:7168
	global_load_lds_dwordx4 v146, s[46:47]
	s_add_i32 m0, s5, 0xe000
	s_nop 0
	global_load_lds_dwordx4 v144, s[46:47]
	s_waitcnt vmcnt(8)
	s_waitcnt lgkmcnt(0)
	s_barrier
	s_setprio 1
	v_mfma_f32_16x16x32_bf16 v[122:125], v[130:133], v[178:181], v[122:125]
	v_mfma_f32_16x16x32_bf16 v[126:129], v[138:141], v[178:181], v[126:129]
	v_mfma_f32_16x16x32_bf16 v[110:113], v[130:133], v[192:195], v[110:113]
	v_mfma_f32_16x16x32_bf16 v[106:109], v[138:141], v[192:195], v[106:109]
	v_mfma_f32_16x16x32_bf16 v[94:97], v[130:133], v[200:203], v[94:97]
	v_mfma_f32_16x16x32_bf16 v[90:93], v[138:141], v[200:203], v[90:93]
	v_mfma_f32_16x16x32_bf16 v[78:81], v[130:133], v[208:211], v[78:81]
	v_mfma_f32_16x16x32_bf16 v[74:77], v[138:141], v[208:211], v[74:77]
	v_mfma_f32_16x16x32_bf16 v[122:125], v[134:137], v[182:185], v[122:125]
	v_mfma_f32_16x16x32_bf16 v[126:129], v[154:157], v[182:185], v[126:129]
	v_mfma_f32_16x16x32_bf16 v[110:113], v[134:137], v[196:199], v[110:113]
	v_mfma_f32_16x16x32_bf16 v[106:109], v[154:157], v[196:199], v[106:109]
	v_mfma_f32_16x16x32_bf16 v[94:97], v[134:137], v[204:207], v[94:97]
	v_mfma_f32_16x16x32_bf16 v[90:93], v[154:157], v[204:207], v[90:93]
	v_mfma_f32_16x16x32_bf16 v[78:81], v[134:137], v[212:215], v[78:81]
	v_mfma_f32_16x16x32_bf16 v[74:77], v[154:157], v[212:215], v[74:77]
	v_mfma_f32_16x16x32_bf16 v[118:121], v[162:165], v[178:181], v[118:121]
	v_mfma_f32_16x16x32_bf16 v[114:117], v[170:173], v[178:181], v[114:117]
	v_mfma_f32_16x16x32_bf16 v[102:105], v[162:165], v[192:195], v[102:105]
	v_mfma_f32_16x16x32_bf16 v[98:101], v[170:173], v[192:195], v[98:101]
	v_mfma_f32_16x16x32_bf16 v[86:89], v[162:165], v[200:203], v[86:89]
	v_mfma_f32_16x16x32_bf16 v[82:85], v[170:173], v[200:203], v[82:85]
	v_mfma_f32_16x16x32_bf16 v[70:73], v[162:165], v[208:211], v[70:73]
	v_mfma_f32_16x16x32_bf16 v[66:69], v[170:173], v[208:211], v[66:69]
	v_mfma_f32_16x16x32_bf16 v[118:121], v[166:169], v[182:185], v[118:121]
	v_mfma_f32_16x16x32_bf16 v[114:117], v[174:177], v[182:185], v[114:117]
	v_mfma_f32_16x16x32_bf16 v[102:105], v[166:169], v[196:199], v[102:105]
	v_mfma_f32_16x16x32_bf16 v[98:101], v[174:177], v[196:199], v[98:101]
	v_mfma_f32_16x16x32_bf16 v[86:89], v[166:169], v[204:207], v[86:89]
	v_mfma_f32_16x16x32_bf16 v[82:85], v[174:177], v[204:207], v[82:85]
	v_mfma_f32_16x16x32_bf16 v[70:73], v[166:169], v[212:215], v[70:73]
	v_mfma_f32_16x16x32_bf16 v[66:69], v[174:177], v[212:215], v[66:69]
	s_setprio 0
	s_barrier
	s_add_i32 s1, s1, s4
	s_mov_b32 m0, s1
	ds_read_b128 v[178:181], v161 offset:16384
	ds_read_b128 v[182:185], v161 offset:17408
	ds_read_b128 v[192:195], v161 offset:18432
	ds_read_b128 v[196:199], v161 offset:19456
	ds_read_b128 v[200:203], v161 offset:20480
	ds_read_b128 v[204:207], v161 offset:21504
	ds_read_b128 v[208:211], v161 offset:22528
	ds_read_b128 v[212:215], v161 offset:23552
	global_load_lds_dwordx4 v0, s[62:63]
	s_add_i32 m0, s1, 0x2000
	s_add_u32 s46, s62, s18
	s_addc_u32 s47, s63, s19
	s_add_i32 s1, s61, s4
	global_load_lds_dwordx4 v142, s[62:63]
	s_mov_b32 m0, s1
	s_nop 0
	global_load_lds_dwordx4 v0, s[46:47]
	s_add_i32 m0, s1, 0x2000
	s_nop 0
	global_load_lds_dwordx4 v142, s[46:47]
	s_mov_b32 m0, s5
	s_nop 0
	global_load_lds_dwordx4 v146, s[50:51]
	s_mov_b32 m0, s52
	s_nop 0
	global_load_lds_dwordx4 v144, s[50:51]
	s_waitcnt vmcnt(8)
	s_waitcnt lgkmcnt(0)
	s_barrier
; #define PG8_STAGE(bufoff, gbase, voff) do { _Pragma("unroll") for (int _i = 0; _i < 2; ++_i) \
;         __builtin_amdgcn_global_load_lds((const unsigned*)((const char*)(gbase) + (voff)[_i]), (LAS unsigned*)(lds + (bufoff) + ldsw + _i * 8192), 16, 0, 0); } while (0)
; #define PG8_LDA(dst, b, h) do { _Pragma("unroll") for (int m = 0; m < 4; ++m) _Pragma("unroll") for (int k = 0; k < 2; ++k) dst[m][k] = *(const LAS bf16x8*)(lds + PG8_SA(b, h) + aoff + m * 2048 + k * 1024); } while (0)
; #define PG8_LDB(dst, b, h) do { _Pragma("unroll") for (int n = 0; n < 2; ++n) _Pragma("unroll") for (int k = 0; k < 2; ++k) dst[n][k] = *(const LAS bf16x8*)(lds + PG8_SB(b, h) + boff + n * 2048 + k * 1024); } while (0)
; #define PG8_MMA(ai, bj, At, Bt) do { __builtin_amdgcn_s_setprio(1); _Pragma("unroll") for (int m = 0; m < 4; ++m) _Pragma("unroll") for (int n = 0; n < 2; ++n) _Pragma("unroll") for (int k = 0; k < 2; ++k) \
;         acc[ai][bj][m][n] = __builtin_amdgcn_mfma_f32_16x16x32_bf16(Bt[n][k], At[m][k], acc[ai][bj][m][n], 0, 0, 0); __builtin_amdgcn_s_setprio(0); } while (0)
; #define PG8_WAIT_V(n) asm volatile("s_waitcnt vmcnt(" #n ")" ::: "memory")
; #define PG8_WAIT_L(n) asm volatile("s_waitcnt lgkmcnt(" #n ")" ::: "memory")
; #define PG8_BAR __builtin_amdgcn_s_barrier()
; #define PG8_SCHED __builtin_amdgcn_sched_barrier(0)
; template <class Epi, class Sched>
; __device__ __forceinline__ void gemm_phase(LAS unsigned char* lds, const Gemm g, const Sched& S, const Epi& E) {
;     ...
;             PG8_WAIT_V(8); PG8_WAIT_L(0); PG8_BAR; PG8_MMA(1, 0, At, B0); PG8_MMA(1, 1, At, B1); PG8_BAR; PG8_SCHED;
;             PG8_LDB(B0, 1, 0); PG8_LDB(B1, 1, 1); PG8_SCHED; PG8_LDA(At, 1, 0); PG8_STAGE(PG8_SA(0, 1), a2 + hstep, voffA);
;             PG8_WAIT_V(8); PG8_WAIT_L(0); PG8_BAR; PG8_MMA(0, 0, At, B0); PG8_MMA(0, 1, At, B1); PG8_BAR; PG8_SCHED;
	s_setprio 1
	v_mfma_f32_16x16x32_bf16 v[62:65], v[130:133], v[178:181], v[62:65]
	v_mfma_f32_16x16x32_bf16 v[58:61], v[138:141], v[178:181], v[58:61]
	v_mfma_f32_16x16x32_bf16 v[46:49], v[130:133], v[192:195], v[46:49]
	v_mfma_f32_16x16x32_bf16 v[42:45], v[138:141], v[192:195], v[42:45]
	v_mfma_f32_16x16x32_bf16 v[30:33], v[130:133], v[200:203], v[30:33]
	v_mfma_f32_16x16x32_bf16 v[26:29], v[138:141], v[200:203], v[26:29]
	v_mfma_f32_16x16x32_bf16 v[14:17], v[130:133], v[208:211], v[14:17]
	v_mfma_f32_16x16x32_bf16 v[10:13], v[138:141], v[208:211], v[10:13]
	v_mfma_f32_16x16x32_bf16 v[62:65], v[134:137], v[182:185], v[62:65]
	v_mfma_f32_16x16x32_bf16 v[58:61], v[154:157], v[182:185], v[58:61]
	v_mfma_f32_16x16x32_bf16 v[46:49], v[134:137], v[196:199], v[46:49]
	v_mfma_f32_16x16x32_bf16 v[42:45], v[154:157], v[196:199], v[42:45]
	v_mfma_f32_16x16x32_bf16 v[30:33], v[134:137], v[204:207], v[30:33]
	v_mfma_f32_16x16x32_bf16 v[26:29], v[154:157], v[204:207], v[26:29]
	v_mfma_f32_16x16x32_bf16 v[14:17], v[134:137], v[212:215], v[14:17]
	v_mfma_f32_16x16x32_bf16 v[10:13], v[154:157], v[212:215], v[10:13]
	v_mfma_f32_16x16x32_bf16 v[54:57], v[162:165], v[178:181], v[54:57]
	v_mfma_f32_16x16x32_bf16 v[50:53], v[170:173], v[178:181], v[50:53]
	v_mfma_f32_16x16x32_bf16 v[38:41], v[162:165], v[192:195], v[38:41]
	v_mfma_f32_16x16x32_bf16 v[34:37], v[170:173], v[192:195], v[34:37]
	v_mfma_f32_16x16x32_bf16 v[22:25], v[162:165], v[200:203], v[22:25]
	v_mfma_f32_16x16x32_bf16 v[18:21], v[170:173], v[200:203], v[18:21]
	v_mfma_f32_16x16x32_bf16 v[6:9], v[162:165], v[208:211], v[6:9]
	v_mfma_f32_16x16x32_bf16 v[2:5], v[170:173], v[208:211], v[2:5]
	v_mfma_f32_16x16x32_bf16 v[54:57], v[166:169], v[182:185], v[54:57]
	v_mfma_f32_16x16x32_bf16 v[50:53], v[174:177], v[182:185], v[50:53]
	v_mfma_f32_16x16x32_bf16 v[38:41], v[166:169], v[196:199], v[38:41]
	v_mfma_f32_16x16x32_bf16 v[34:37], v[174:177], v[196:199], v[34:37]
	v_mfma_f32_16x16x32_bf16 v[22:25], v[166:169], v[204:207], v[22:25]
	v_mfma_f32_16x16x32_bf16 v[18:21], v[174:177], v[204:207], v[18:21]
	v_mfma_f32_16x16x32_bf16 v[6:9], v[166:169], v[212:215], v[6:9]
	v_mfma_f32_16x16x32_bf16 v[2:5], v[174:177], v[212:215], v[2:5]
	s_setprio 0
	s_barrier
	s_add_i32 s1, 0, 0x18000
	s_add_i32 s61, 0, 0x1c000
	v_add_u32_e32 v154, s1, v160
	v_add_u32_e32 v174, s61, v160
	ds_read_b128 v[130:133], v154
	ds_read_b128 v[134:137], v154 offset:1024
	ds_read_b128 v[138:141], v154 offset:2048
	ds_read_b128 v[154:157], v154 offset:3072
	ds_read_b128 v[162:165], v174
	ds_read_b128 v[166:169], v174 offset:1024
	ds_read_b128 v[170:173], v174 offset:2048
	ds_read_b128 v[174:177], v174 offset:3072
	s_add_u32 s46, s50, s18
	s_addc_u32 s47, s51, s19
	s_mov_b32 m0, s53
	ds_read_b128 v[178:181], v161 offset:32768
	ds_read_b128 v[182:185], v161 offset:33792
	ds_read_b128 v[192:195], v161 offset:34816
	ds_read_b128 v[196:199], v161 offset:35840
	ds_read_b128 v[200:203], v161 offset:36864
	ds_read_b128 v[204:207], v161 offset:37888
	ds_read_b128 v[208:211], v161 offset:38912
	ds_read_b128 v[212:215], v161 offset:39936
	global_load_lds_dwordx4 v146, s[46:47]
	s_mov_b32 m0, s54
	s_nop 0
	global_load_lds_dwordx4 v144, s[46:47]
	s_waitcnt vmcnt(8)
	s_waitcnt lgkmcnt(0)
	s_barrier
	s_setprio 1
	v_mfma_f32_16x16x32_bf16 v[122:125], v[130:133], v[178:181], v[122:125]
	v_mfma_f32_16x16x32_bf16 v[126:129], v[138:141], v[178:181], v[126:129]
	v_mfma_f32_16x16x32_bf16 v[110:113], v[130:133], v[192:195], v[110:113]
	v_mfma_f32_16x16x32_bf16 v[106:109], v[138:141], v[192:195], v[106:109]
	v_mfma_f32_16x16x32_bf16 v[94:97], v[130:133], v[200:203], v[94:97]
	v_mfma_f32_16x16x32_bf16 v[90:93], v[138:141], v[200:203], v[90:93]
	v_mfma_f32_16x16x32_bf16 v[78:81], v[130:133], v[208:211], v[78:81]
	v_mfma_f32_16x16x32_bf16 v[74:77], v[138:141], v[208:211], v[74:77]
	v_mfma_f32_16x16x32_bf16 v[122:125], v[134:137], v[182:185], v[122:125]
	v_mfma_f32_16x16x32_bf16 v[126:129], v[154:157], v[182:185], v[126:129]
	v_mfma_f32_16x16x32_bf16 v[110:113], v[134:137], v[196:199], v[110:113]
	v_mfma_f32_16x16x32_bf16 v[106:109], v[154:157], v[196:199], v[106:109]
	v_mfma_f32_16x16x32_bf16 v[94:97], v[134:137], v[204:207], v[94:97]
	v_mfma_f32_16x16x32_bf16 v[90:93], v[154:157], v[204:207], v[90:93]
	v_mfma_f32_16x16x32_bf16 v[78:81], v[134:137], v[212:215], v[78:81]
	v_mfma_f32_16x16x32_bf16 v[74:77], v[154:157], v[212:215], v[74:77]
	v_mfma_f32_16x16x32_bf16 v[118:121], v[162:165], v[178:181], v[118:121]
	v_mfma_f32_16x16x32_bf16 v[114:117], v[170:173], v[178:181], v[114:117]
	v_mfma_f32_16x16x32_bf16 v[102:105], v[162:165], v[192:195], v[102:105]
	v_mfma_f32_16x16x32_bf16 v[98:101], v[170:173], v[192:195], v[98:101]
	v_mfma_f32_16x16x32_bf16 v[86:89], v[162:165], v[200:203], v[86:89]
	v_mfma_f32_16x16x32_bf16 v[82:85], v[170:173], v[200:203], v[82:85]
	v_mfma_f32_16x16x32_bf16 v[70:73], v[162:165], v[208:211], v[70:73]
	v_mfma_f32_16x16x32_bf16 v[66:69], v[170:173], v[208:211], v[66:69]
	v_mfma_f32_16x16x32_bf16 v[118:121], v[166:169], v[182:185], v[118:121]
	v_mfma_f32_16x16x32_bf16 v[114:117], v[174:177], v[182:185], v[114:117]
	v_mfma_f32_16x16x32_bf16 v[102:105], v[166:169], v[196:199], v[102:105]
	v_mfma_f32_16x16x32_bf16 v[98:101], v[174:177], v[196:199], v[98:101]
	v_mfma_f32_16x16x32_bf16 v[86:89], v[166:169], v[204:207], v[86:89]
	v_mfma_f32_16x16x32_bf16 v[82:85], v[174:177], v[204:207], v[82:85]
	v_mfma_f32_16x16x32_bf16 v[70:73], v[166:169], v[212:215], v[70:73]
	v_mfma_f32_16x16x32_bf16 v[66:69], v[174:177], v[212:215], v[66:69]
	s_setprio 0
	s_barrier
; #define PG8_STAGE(bufoff, gbase, voff) do { _Pragma("unroll") for (int _i = 0; _i < 2; ++_i) \
;         __builtin_amdgcn_global_load_lds((const unsigned*)((const char*)(gbase) + (voff)[_i]), (LAS unsigned*)(lds + (bufoff) + ldsw + _i * 8192), 16, 0, 0); } while (0)
; #define PG8_LDA(dst, b, h) do { _Pragma("unroll") for (int m = 0; m < 4; ++m) _Pragma("unroll") for (int k = 0; k < 2; ++k) dst[m][k] = *(const LAS bf16x8*)(lds + PG8_SA(b, h) + aoff + m * 2048 + k * 1024); } while (0)
; #define PG8_MMA(ai, bj, At, Bt) do { __builtin_amdgcn_s_setprio(1); _Pragma("unroll") for (int m = 0; m < 4; ++m) _Pragma("unroll") for (int n = 0; n < 2; ++n) _Pragma("unroll") for (int k = 0; k < 2; ++k) \
;         acc[ai][bj][m][n] = __builtin_amdgcn_mfma_f32_16x16x32_bf16(Bt[n][k], At[m][k], acc[ai][bj][m][n], 0, 0, 0); __builtin_amdgcn_s_setprio(0); } while (0)
; #define PG8_WAIT_V(n) asm volatile("s_waitcnt vmcnt(" #n ")" ::: "memory")
; #define PG8_WAIT_L(n) asm volatile("s_waitcnt lgkmcnt(" #n ")" ::: "memory")
; #define PG8_BAR __builtin_amdgcn_s_barrier()
; #define PG8_SCHED __builtin_amdgcn_sched_barrier(0)
; template <class Epi, class Sched>
; __device__ __forceinline__ void gemm_phase(LAS unsigned char* lds, const Gemm g, const Sched& S, const Epi& E) {
;     ...
;             PG8_LDA(At, 1, 1); PG8_STAGE(PG8_SB(1, 0), b3, voffB); PG8_STAGE(PG8_SB(1, 1), b3 + hstep, voffB); PG8_STAGE(PG8_SA(1, 0), a3, voffA);
;             PG8_WAIT_V(8); PG8_WAIT_L(0); PG8_BAR; PG8_MMA(1, 0, At, B0); PG8_MMA(1, 1, At, B1); PG8_BAR; PG8_SCHED;
;         }
	s_add_i32 s1, s1, s4
	s_add_u32 s46, s62, 0x80
	s_addc_u32 s47, s63, 0
	s_mov_b32 m0, s1
	ds_read_b128 v[178:181], v161 offset:49152
	ds_read_b128 v[182:185], v161 offset:50176
	ds_read_b128 v[192:195], v161 offset:51200
	ds_read_b128 v[196:199], v161 offset:52224
	ds_read_b128 v[200:203], v161 offset:53248
	ds_read_b128 v[204:207], v161 offset:54272
	ds_read_b128 v[208:211], v161 offset:55296
	ds_read_b128 v[212:215], v161 offset:56320
	global_load_lds_dwordx4 v0, s[46:47]
	s_add_i32 m0, s1, 0x2000
	s_add_i32 s1, s61, s4
	global_load_lds_dwordx4 v142, s[46:47]
	s_add_u32 s46, s46, s18
	s_addc_u32 s47, s47, s19
	s_mov_b32 m0, s1
	s_nop 0
	global_load_lds_dwordx4 v0, s[46:47]
	s_add_i32 m0, s1, 0x2000
	s_nop 0
	global_load_lds_dwordx4 v142, s[46:47]
	s_add_u32 s46, s50, 0x80
	s_addc_u32 s47, s51, 0
	s_mov_b32 m0, s55
	s_nop 0
	global_load_lds_dwordx4 v146, s[46:47]
	s_mov_b32 m0, s56
	s_nop 0
	global_load_lds_dwordx4 v144, s[46:47]
	s_waitcnt vmcnt(8)
	s_waitcnt lgkmcnt(0)
	s_barrier
	s_setprio 1
	v_mfma_f32_16x16x32_bf16 v[62:65], v[130:133], v[178:181], v[62:65]
	v_mfma_f32_16x16x32_bf16 v[58:61], v[138:141], v[178:181], v[58:61]
	v_mfma_f32_16x16x32_bf16 v[46:49], v[130:133], v[192:195], v[46:49]
	v_mfma_f32_16x16x32_bf16 v[42:45], v[138:141], v[192:195], v[42:45]
	v_mfma_f32_16x16x32_bf16 v[30:33], v[130:133], v[200:203], v[30:33]
	v_mfma_f32_16x16x32_bf16 v[26:29], v[138:141], v[200:203], v[26:29]
	v_mfma_f32_16x16x32_bf16 v[14:17], v[130:133], v[208:211], v[14:17]
	v_mfma_f32_16x16x32_bf16 v[10:13], v[138:141], v[208:211], v[10:13]
	v_mfma_f32_16x16x32_bf16 v[62:65], v[134:137], v[182:185], v[62:65]
	v_mfma_f32_16x16x32_bf16 v[58:61], v[154:157], v[182:185], v[58:61]
	v_mfma_f32_16x16x32_bf16 v[46:49], v[134:137], v[196:199], v[46:49]
	v_mfma_f32_16x16x32_bf16 v[42:45], v[154:157], v[196:199], v[42:45]
	v_mfma_f32_16x16x32_bf16 v[30:33], v[134:137], v[204:207], v[30:33]
	v_mfma_f32_16x16x32_bf16 v[26:29], v[154:157], v[204:207], v[26:29]
	v_mfma_f32_16x16x32_bf16 v[14:17], v[134:137], v[212:215], v[14:17]
	v_mfma_f32_16x16x32_bf16 v[10:13], v[154:157], v[212:215], v[10:13]
	v_mfma_f32_16x16x32_bf16 v[54:57], v[162:165], v[178:181], v[54:57]
	v_mfma_f32_16x16x32_bf16 v[50:53], v[170:173], v[178:181], v[50:53]
	v_mfma_f32_16x16x32_bf16 v[38:41], v[162:165], v[192:195], v[38:41]
	v_mfma_f32_16x16x32_bf16 v[34:37], v[170:173], v[192:195], v[34:37]
	v_mfma_f32_16x16x32_bf16 v[22:25], v[162:165], v[200:203], v[22:25]
	v_mfma_f32_16x16x32_bf16 v[18:21], v[170:173], v[200:203], v[18:21]
	v_mfma_f32_16x16x32_bf16 v[6:9], v[162:165], v[208:211], v[6:9]
	v_mfma_f32_16x16x32_bf16 v[2:5], v[170:173], v[208:211], v[2:5]
	v_mfma_f32_16x16x32_bf16 v[54:57], v[166:169], v[182:185], v[54:57]
	v_mfma_f32_16x16x32_bf16 v[50:53], v[174:177], v[182:185], v[50:53]
	v_mfma_f32_16x16x32_bf16 v[38:41], v[166:169], v[196:199], v[38:41]
	v_mfma_f32_16x16x32_bf16 v[34:37], v[174:177], v[196:199], v[34:37]
	v_mfma_f32_16x16x32_bf16 v[22:25], v[166:169], v[204:207], v[22:25]
	v_mfma_f32_16x16x32_bf16 v[18:21], v[174:177], v[204:207], v[18:21]
	v_mfma_f32_16x16x32_bf16 v[6:9], v[166:169], v[212:215], v[6:9]
	v_mfma_f32_16x16x32_bf16 v[2:5], v[174:177], v[212:215], v[2:5]
	s_setprio 0
	s_barrier
	s_cmp_ge_i32 s60, s57
	s_mov_b64 s[46:47], s[48:49]
	s_mov_b32 s50, s60
	s_cbranch_scc0 .LBB0_450
